# scan loops: 48 of the 64 dot-product terms per step now v_pk_fma_f32 on scalar-loaded kk (3 SGPR slots loaded one step ahead), rest DPP; on top of previous best
# speedup vs baseline: 1.0028x; 1.0028x over previous
; __device__ __forceinline__ const float* uni_ptr(const float* p) { const unsigned long long v = (unsigned long long)p; const unsigned lo = __builtin_amdgcn_readfirstlane((unsigned)v), hi = __builtin_amdgcn_readfirstlane((unsigned)(v >> 32)); return (const float*)(((unsigned long long)hi << 32) | lo); }
; template <bool SK>
; __device__ __forceinline__ void scan_task(const float* R, const float* W, const float* KX, const float* KK, const float* KKA, const float* V, float* OUT, float* STT, const float* S0, float* SOUT, int nstep, int lane) {
;     float s[64];
;     if (S0) {
; #pragma unroll
;         for (int k4 = 0; k4 < 16; ++k4) { const f32x4 v = *(const f32x4*)(S0 + lane * 64 + 4 * k4); s[4 * k4] = v[0]; s[4 * k4 + 1] = v[1]; s[4 * k4 + 2] = v[2]; s[4 * k4 + 3] = v[3]; }
;     } else {
; #pragma unroll
;         for (int k = 0; k < 64; ++k) s[k] = SK ? 0.f : (k == lane ? 1.f : 0.f);
;     }
; __device__ __forceinline__ void scan_item(Frame& F, int l, int item, unsigned char* ws) {
;     const int b = item >> 7, chunk = (item >> 1) & 63, hq = item & 1, h = hq * 4 + (F.wave & 3);
;     const size_t ro = ((size_t)(b * SEQ + chunk * 64)) * BW + h * 64; const size_t so = ((size_t)((b * 8 + h) * 64 + chunk)) * 4096;
;     const float* R = (const float*)(ws + WS_R + l * SZ_RWL) + ro; const float* W = (const float*)(ws + WS_W + l * SZ_RWL) + ro; const float* KX = (const float*)(ws + WS_KX + l * SZ_RWL) + ro;
;     const float* KK = (const float*)(ws + WS_KK + l * SZ_RWL) + ro; const float* KKA = (const float*)(ws + WS_KKA + l * SZ_RWL) + ro; const float* V = (const float*)(ws + WS_V) + ro;
;     if (F.wave >> 2) scan_task<true>(uni_ptr(R), uni_ptr(W), uni_ptr(KX), uni_ptr(KK), uni_ptr(KKA), V, (float*)(ws + WS_OL) + ro, (float*)(ws + WS_LC) + so, nullptr, nullptr, 64, F.lane);
.LBB0_904:
	s_mov_b64 s[8:9], s[62:63]
	s_mov_b32 s1, s66
	v_mov_b32_e32 v68, v210
	s_mov_b32 s2, s97
	v_mov_b32_e32 v1, v0
	s_mov_b32 s0, s94
	s_nop 0
	v_readlane_b32 s2, v252, 14
	v_readlane_b32 s3, v252, 15
	s_andn2_b64 vcc, exec, s[2:3]
	s_cbranch_vccnz .LBB0_903
	s_lshl_b32 s2, s29, 6
	s_bfe_u32 s4, s24, 0x60001
	s_and_b32 s7, s2, 0x100
	s_ashr_i32 s5, s24, 7
	s_lshl_b32 s2, s24, 2
	v_and_b32_e64 v1, s0, 3
	s_lshl_b32 s28, s4, 6
	v_readfirstlane_b32 s25, v1
	v_and_or_b32 v1, s2, 4, v1
	s_lshl_b32 s33, s5, 12
	s_lshl_b32 s5, s5, 9
	s_or_b32 s2, s28, s33
	v_lshl_or_b32 v2, v1, 6, s5
	s_ashr_i32 s3, s2, 31
	v_or_b32_e32 v2, s4, v2
	s_waitcnt lgkmcnt(0)
	v_ashrrev_i32_e32 v3, 31, v2
	s_mul_hi_i32 s4, s1, 0x1100000
	s_mul_i32 s1, s1, 0x1100000
	s_lshl_b64 s[2:3], s[2:3], 11
	v_lshlrev_b64 v[70:71], 12, v[2:3]
	v_lshl_or_b32 v2, v1, 8, s2
	s_add_u32 s2, s8, s1
	v_mov_b32_e32 v3, s3
	s_addc_u32 s3, s9, s4
	v_lshl_add_u64 v[2:3], s[2:3], 0, v[2:3]
	s_mov_b64 s[2:3], 0x34c00000
	v_lshl_add_u64 v[10:11], v[2:3], 0, s[2:3]
	s_mov_b64 s[2:3], 0x36e00000
	v_lshl_add_u64 v[8:9], v[2:3], 0, s[2:3]
	s_mov_b64 s[2:3], 0x39000000
	v_lshl_add_u64 v[6:7], v[2:3], 0, s[2:3]
	s_mov_b64 s[2:3], 0x3c300000
	v_lshl_add_u64 v[4:5], v[2:3], 0, s[2:3]
	s_mov_b64 s[2:3], 0x3e500000
	v_lshl_add_u64 v[2:3], v[2:3], 0, s[2:3]
	v_cmp_lt_u32_e64 s[2:3], s0, 4
	s_mov_b64 s[0:1], -1
	s_and_b64 s[2:3], s[2:3], exec
	v_ashrrev_i32_e32 v69, 31, v68
	s_cbranch_scc1 .LBB0_909
	s_add_i32 s4, s33, s28
	s_lshl_b32 s6, s25, 6
	s_ashr_i32 s5, s4, 31
	s_add_i32 s6, s7, s6
	s_lshl_b64 s[4:5], s[4:5], 11
	s_lshl_b32 s6, s6, 2
	v_writelane_b32 v255, s7, 27
	s_add_u32 s6, s8, s6
	v_writelane_b32 v255, s8, 23
	s_addc_u32 s7, s9, 0
	s_add_u32 s4, s6, s4
	s_addc_u32 s5, s7, s5
	v_readfirstlane_b32 s27, v11
	v_readfirstlane_b32 s26, v10
	v_readfirstlane_b32 s35, v9
	v_readfirstlane_b32 s34, v8
	v_readfirstlane_b32 s3, v7
	v_readfirstlane_b32 s2, v6
	v_readfirstlane_b32 s37, v5
	v_readfirstlane_b32 s36, v4
	v_readfirstlane_b32 s1, v3
	v_readfirstlane_b32 s0, v2
	v_lshl_add_u64 v[12:13], v[68:69], 2, s[4:5]
	s_mov_b64 s[4:5], 0x3b200000
	v_mov_b32_e32 v1, 0
	v_writelane_b32 v255, s9, 24
	s_waitcnt vmcnt(0)
	v_lshl_add_u64 v[52:53], v[12:13], 0, s[4:5]
	s_mov_b32 s31, 0
	s_mov_b64 s[96:97], s[36:37]
	s_mov_b64 s[90:91], s[34:35]
	s_mov_b64 s[94:95], s[0:1]
	s_mov_b64 s[92:93], s[2:3]
	s_mov_b64 s[88:89], s[26:27]
	v_mov_b32_e32 v88, 0
	v_mov_b32_e32 v89, 0
	v_mov_b32_e32 v90, 0
	v_mov_b32_e32 v91, 0
	v_mov_b32_e32 v82, 0
	v_mov_b32_e32 v83, v1
	v_mov_b32_e32 v12, 0
	v_mov_b32_e32 v13, v1
	v_mov_b32_e32 v14, 0
	v_mov_b32_e32 v15, v1
	v_mov_b32_e32 v16, 0
	v_mov_b32_e32 v17, v1
	v_mov_b32_e32 v18, 0
	v_mov_b32_e32 v19, v1
	v_mov_b32_e32 v20, 0
	v_mov_b32_e32 v21, v1
	v_mov_b32_e32 v22, 0
	v_mov_b32_e32 v23, v1
	v_mov_b32_e32 v24, 0
	v_mov_b32_e32 v25, v1
	v_mov_b32_e32 v26, 0
	v_mov_b32_e32 v27, v1
	v_mov_b32_e32 v28, 0
	v_mov_b32_e32 v29, v1
	v_mov_b32_e32 v30, 0
	v_mov_b32_e32 v31, v1
	v_mov_b32_e32 v32, 0
	v_mov_b32_e32 v33, v1
	v_mov_b32_e32 v36, 0
	v_mov_b32_e32 v37, v1
	v_mov_b32_e32 v38, 0
	v_mov_b32_e32 v39, v1
	v_mov_b32_e32 v40, 0
	v_mov_b32_e32 v41, v1
	v_mov_b32_e32 v42, 0
	v_mov_b32_e32 v43, v1
	v_mov_b32_e32 v44, 0
	v_mov_b32_e32 v45, v1
	v_mov_b32_e32 v46, 0
	v_mov_b32_e32 v47, v1
	v_mov_b32_e32 v48, 0
	v_mov_b32_e32 v49, v1
	v_mov_b32_e32 v50, 0
	v_mov_b32_e32 v51, v1
	v_mov_b32_e32 v54, 0
	v_mov_b32_e32 v55, v1
	v_mov_b32_e32 v56, 0
	v_mov_b32_e32 v57, v1
	v_mov_b32_e32 v58, 0
	v_mov_b32_e32 v59, v1
	v_mov_b32_e32 v60, 0
	v_mov_b32_e32 v61, v1
	v_mov_b32_e32 v62, 0
	v_mov_b32_e32 v63, v1
	v_mov_b32_e32 v64, 0
	v_mov_b32_e32 v65, v1
	v_mov_b32_e32 v66, 0
	v_mov_b32_e32 v67, v1
	v_mov_b32_e32 v72, 0
	v_mov_b32_e32 v73, v1
	v_mov_b32_e32 v74, 0
	v_mov_b32_e32 v75, v1
	v_mov_b32_e32 v76, 0
	v_mov_b32_e32 v77, v1
	v_mov_b32_e32 v78, 0
	v_mov_b32_e32 v79, v1
	v_mov_b32_e32 v80, 0
	v_mov_b32_e32 v81, v1
	s_mov_b32 s30, 0x6600000
	s_mov_b64 s[38:39], 0x800
	v_readlane_b32 s30, v251, 3
	s_nop 3
	s_mul_i32 s30, s30, 0x3800
	s_nop 0
	v_lshl_add_u32 v1, v68, 2, s30
	ds_write_b32 v1, v92 offset:0
	ds_write_b32 v1, v93 offset:256
	ds_write_b32 v1, v94 offset:512
	ds_write_b32 v1, v95 offset:768
	ds_write_b32 v1, v96 offset:1024
	ds_write_b32 v1, v97 offset:1280
	ds_write_b32 v1, v98 offset:1536
	ds_write_b32 v1, v99 offset:1792
	ds_write_b32 v1, v100 offset:2048
	ds_write_b32 v1, v101 offset:2304
	ds_write_b32 v1, v102 offset:2560
	ds_write_b32 v1, v103 offset:2816
	ds_write_b32 v1, v104 offset:3072
	ds_write_b32 v1, v105 offset:3328
	ds_write_b32 v1, v106 offset:3584
	ds_write_b32 v1, v107 offset:3840
	ds_write_b32 v1, v108 offset:4096
	ds_write_b32 v1, v109 offset:4352
	ds_write_b32 v1, v110 offset:4608
	ds_write_b32 v1, v111 offset:4864
	ds_write_b32 v1, v112 offset:5120
	ds_write_b32 v1, v113 offset:5376
	ds_write_b32 v1, v114 offset:5632
	ds_write_b32 v1, v115 offset:5888
	ds_write_b32 v1, v116 offset:6144
	ds_write_b32 v1, v117 offset:6400
	ds_write_b32 v1, v118 offset:6656
	ds_write_b32 v1, v119 offset:6912
	ds_write_b32 v1, v120 offset:7168
	ds_write_b32 v1, v121 offset:7424
	ds_write_b32 v1, v122 offset:7680
	ds_write_b32 v1, v123 offset:7936
	ds_write_b32 v1, v124 offset:8192
	ds_write_b32 v1, v125 offset:8448
	ds_write_b32 v1, v126 offset:8704
	ds_write_b32 v1, v127 offset:8960
	ds_write_b32 v1, v128 offset:9216
	ds_write_b32 v1, v129 offset:9472
	ds_write_b32 v1, v130 offset:9728
	ds_write_b32 v1, v131 offset:9984
	ds_write_b32 v1, v132 offset:10240
	ds_write_b32 v1, v133 offset:10496
	ds_write_b32 v1, v134 offset:10752
	ds_write_b32 v1, v135 offset:11008
	ds_write_b32 v1, v136 offset:11264
	ds_write_b32 v1, v137 offset:11520
	ds_write_b32 v1, v138 offset:11776
	ds_write_b32 v1, v139 offset:12032
	ds_write_b32 v1, v140 offset:12288
	ds_write_b32 v1, v141 offset:12544
	ds_write_b32 v1, v142 offset:12800
	ds_write_b32 v1, v143 offset:13056
	ds_write_b32 v1, v144 offset:13312
	ds_write_b32 v1, v145 offset:13568
	v_readfirstlane_b32 s0, v52
	v_readfirstlane_b32 s1, v53
	s_nop 3
	s_add_u32 s2, s0, 0x6600000
	s_addc_u32 s3, s1, 0
	s_waitcnt lgkmcnt(0)
; template <bool SK>
; __device__ __forceinline__ void scan_task(const float* R, const float* W, const float* KX, const float* KK, const float* KKA, const float* V, float* OUT, float* STT, const float* S0, float* SOUT, int nstep, int lane) {
;     ...
;     for (int t = 0; t < nstep; ++t) {
;         asm volatile("" :: "v"(pf0), "v"(pf1), "v"(pf2), "v"(pf3), "v"(pf4));
;         { const int tp = (t + 2 < nstep) ? t + 2 : t; const size_t po = (size_t)tp * BW + lane;
;           pf0 = KK[po]; pf1 = W[po]; pf2 = KKA[po]; pf3 = KX[po]; pf4 = R[po]; }
;         cfloat* kk = (cfloat*)(KK + (size_t)t * BW); cfloat* w = (cfloat*)(W + (size_t)t * BW); cfloat* kka = (cfloat*)(KKA + (size_t)t * BW);
;         cfloat* kx = (cfloat*)(KX + (size_t)t * BW); cfloat* r = (cfloat*)(R + (size_t)t * BW);
;         float d0 = 0.f, d1 = 0.f;
; #pragma unroll
;         for (int k = 0; k < 64; k += 2) { d0 = fmaf(s[k], kk[k], d0); d1 = fmaf(s[k + 1], kk[k + 1], d1); }
;         const float nd = -(d0 + d1);
;         const float vt = SK ? V[(size_t)t * BW + lane] : 0.f;
;         float o0 = 0.f, o1 = 0.f;
; #pragma unroll
;         for (int k = 0; k < 64; k += 2) {
;             float x = s[k] * w[k]; x = fmaf(nd, kka[k], x); if (SK) x = fmaf(vt, kx[k], x); s[k] = x; o0 = fmaf(x, r[k], o0);
	v_mov_b32_e32 v145, v1
	v_and_b32_e32 v143, 15, v68
	v_lshlrev_b32_e32 v143, 4, v143
	v_lshlrev_b32_e32 v144, 2, v68
	s_nop 0
	s_mov_b64 s[34:35], s[96:97]
	s_load_dwordx16 s[4:19], s[34:35], 0x0
	s_load_dwordx16 s[40:55], s[34:35], 0x40
	s_load_dwordx16 s[56:71], s[34:35], 0x80
	global_load_dwordx4 v[92:95], v143, s[96:97]
	global_load_dwordx4 v[96:99], v143, s[90:91]
	global_load_dwordx4 v[100:103], v143, s[94:95]
	global_load_dwordx4 v[104:107], v143, s[92:93]
	global_load_dwordx4 v[108:111], v143, s[88:89]
	global_load_dword v132, v144, s[0:1]
	global_load_dwordx4 v[112:115], v143, s[96:97] offset:2048
	global_load_dwordx4 v[116:119], v143, s[90:91] offset:2048
	global_load_dwordx4 v[120:123], v143, s[94:95] offset:2048
	global_load_dwordx4 v[124:127], v143, s[92:93] offset:2048
	global_load_dwordx4 v[128:131], v143, s[88:89] offset:2048
	global_load_dword v133, v144, s[0:1] offset:2048
	s_add_u32 s96, s96, 0x1000
	s_addc_u32 s97, s97, 0
	s_add_u32 s90, s90, 0x1000
	s_addc_u32 s91, s91, 0
	s_add_u32 s94, s94, 0x1000
	s_addc_u32 s95, s95, 0
	s_add_u32 s92, s92, 0x1000
	s_addc_u32 s93, s93, 0
	s_add_u32 s88, s88, 0x1000
	s_addc_u32 s89, s89, 0
	s_add_u32 s0, s0, 0x1000
	s_addc_u32 s1, s1, 0
	s_mov_b32 s20, 0
	s_waitcnt vmcnt(0)
.Lscan_s_loop:
	s_waitcnt vmcnt(8) lgkmcnt(0)
	v_pk_mul_f32 v[134:135], v[80:81], s[4:5]
	v_pk_mul_f32 v[136:137], v[78:79], s[6:7]
	v_pk_fma_f32 v[134:135], v[76:77], s[8:9], v[134:135]
	v_pk_fma_f32 v[136:137], v[74:75], s[10:11], v[136:137]
	v_pk_fma_f32 v[134:135], v[72:73], s[12:13], v[134:135]
	v_pk_fma_f32 v[136:137], v[66:67], s[14:15], v[136:137]
	v_pk_fma_f32 v[134:135], v[64:65], s[16:17], v[134:135]
	v_pk_fma_f32 v[136:137], v[62:63], s[18:19], v[136:137]
	v_pk_fma_f32 v[134:135], v[60:61], s[40:41], v[134:135]
	v_pk_fma_f32 v[136:137], v[58:59], s[42:43], v[136:137]
	v_pk_fma_f32 v[134:135], v[56:57], s[44:45], v[134:135]
	v_pk_fma_f32 v[136:137], v[54:55], s[46:47], v[136:137]
	v_pk_fma_f32 v[134:135], v[50:51], s[48:49], v[134:135]
	v_pk_fma_f32 v[136:137], v[48:49], s[50:51], v[136:137]
	v_pk_fma_f32 v[134:135], v[46:47], s[52:53], v[134:135]
	v_pk_fma_f32 v[136:137], v[44:45], s[54:55], v[136:137]
	v_pk_fma_f32 v[134:135], v[42:43], s[56:57], v[134:135]
	v_pk_fma_f32 v[136:137], v[40:41], s[58:59], v[136:137]
	v_pk_fma_f32 v[134:135], v[38:39], s[60:61], v[134:135]
	v_pk_fma_f32 v[136:137], v[36:37], s[62:63], v[136:137]
	v_pk_fma_f32 v[134:135], v[32:33], s[64:65], v[134:135]
	v_pk_fma_f32 v[136:137], v[30:31], s[66:67], v[136:137]
	v_pk_fma_f32 v[134:135], v[28:29], s[68:69], v[134:135]
	v_pk_fma_f32 v[136:137], v[26:27], s[70:71], v[136:137]
	s_nop 0
	v_fmac_f32_dpp v134, v92, v24 row_newbcast:12 row_mask:0xf bank_mask:0xf
	v_fmac_f32_dpp v135, v93, v25 row_newbcast:12 row_mask:0xf bank_mask:0xf
	v_fmac_f32_dpp v136, v94, v22 row_newbcast:12 row_mask:0xf bank_mask:0xf
	v_fmac_f32_dpp v137, v95, v23 row_newbcast:12 row_mask:0xf bank_mask:0xf
	v_fmac_f32_dpp v134, v92, v20 row_newbcast:13 row_mask:0xf bank_mask:0xf
	v_fmac_f32_dpp v135, v93, v21 row_newbcast:13 row_mask:0xf bank_mask:0xf
	v_fmac_f32_dpp v136, v94, v18 row_newbcast:13 row_mask:0xf bank_mask:0xf
	v_fmac_f32_dpp v137, v95, v19 row_newbcast:13 row_mask:0xf bank_mask:0xf
	v_fmac_f32_dpp v134, v92, v16 row_newbcast:14 row_mask:0xf bank_mask:0xf
	v_fmac_f32_dpp v135, v93, v17 row_newbcast:14 row_mask:0xf bank_mask:0xf
	v_fmac_f32_dpp v136, v94, v14 row_newbcast:14 row_mask:0xf bank_mask:0xf
	v_fmac_f32_dpp v137, v95, v15 row_newbcast:14 row_mask:0xf bank_mask:0xf
	v_fmac_f32_dpp v134, v92, v12 row_newbcast:15 row_mask:0xf bank_mask:0xf
	v_fmac_f32_dpp v135, v93, v13 row_newbcast:15 row_mask:0xf bank_mask:0xf
	v_fmac_f32_dpp v136, v94, v82 row_newbcast:15 row_mask:0xf bank_mask:0xf
	v_fmac_f32_dpp v137, v95, v83 row_newbcast:15 row_mask:0xf bank_mask:0xf
	global_load_dwordx4 v[92:95], v143, s[96:97]
	s_add_u32 s34, s34, 0x800
	s_addc_u32 s35, s35, 0
	s_nop 1
	s_load_dwordx16 s[4:19], s[34:35], 0x0
	s_load_dwordx16 s[40:55], s[34:35], 0x40
	s_load_dwordx16 s[56:71], s[34:35], 0x80
	v_add_f32_e32 v134, v134, v136
	v_add_f32_e32 v135, v135, v137
	v_add_f32_e32 v142, v134, v135
	v_xor_b32_e32 v142, 0x80000000, v142
	v_mul_f32_dpp v80, v96, v80 row_newbcast:0 row_mask:0xf bank_mask:0xf
	v_mul_f32_dpp v81, v97, v81 row_newbcast:0 row_mask:0xf bank_mask:0xf
	v_mul_f32_dpp v78, v98, v78 row_newbcast:0 row_mask:0xf bank_mask:0xf
	v_mul_f32_dpp v79, v99, v79 row_newbcast:0 row_mask:0xf bank_mask:0xf
	v_fmac_f32_dpp v80, v100, v142 row_newbcast:0 row_mask:0xf bank_mask:0xf
	v_fmac_f32_dpp v81, v101, v142 row_newbcast:0 row_mask:0xf bank_mask:0xf
	v_fmac_f32_dpp v78, v102, v142 row_newbcast:0 row_mask:0xf bank_mask:0xf
	v_fmac_f32_dpp v79, v103, v142 row_newbcast:0 row_mask:0xf bank_mask:0xf
	v_fmac_f32_dpp v80, v104, v132 row_newbcast:0 row_mask:0xf bank_mask:0xf
	v_fmac_f32_dpp v81, v105, v132 row_newbcast:0 row_mask:0xf bank_mask:0xf
	v_fmac_f32_dpp v78, v106, v132 row_newbcast:0 row_mask:0xf bank_mask:0xf
	v_fmac_f32_dpp v79, v107, v132 row_newbcast:0 row_mask:0xf bank_mask:0xf
	v_mul_f32_dpp v138, v108, v80 row_newbcast:0 row_mask:0xf bank_mask:0xf
	v_mul_f32_dpp v139, v109, v81 row_newbcast:0 row_mask:0xf bank_mask:0xf
	v_mul_f32_dpp v140, v110, v78 row_newbcast:0 row_mask:0xf bank_mask:0xf
	v_mul_f32_dpp v141, v111, v79 row_newbcast:0 row_mask:0xf bank_mask:0xf
	v_mul_f32_dpp v76, v96, v76 row_newbcast:1 row_mask:0xf bank_mask:0xf
	v_mul_f32_dpp v77, v97, v77 row_newbcast:1 row_mask:0xf bank_mask:0xf
	v_mul_f32_dpp v74, v98, v74 row_newbcast:1 row_mask:0xf bank_mask:0xf
	v_mul_f32_dpp v75, v99, v75 row_newbcast:1 row_mask:0xf bank_mask:0xf
; template <bool SK>
; __device__ __forceinline__ void scan_task(const float* R, const float* W, const float* KX, const float* KK, const float* KKA, const float* V, float* OUT, float* STT, const float* S0, float* SOUT, int nstep, int lane) {
;     ...
;         float o0 = 0.f, o1 = 0.f;
; #pragma unroll
;         for (int k = 0; k < 64; k += 2) {
;             float x = s[k] * w[k]; x = fmaf(nd, kka[k], x); if (SK) x = fmaf(vt, kx[k], x); s[k] = x; o0 = fmaf(x, r[k], o0);
;             float y = s[k + 1] * w[k + 1]; y = fmaf(nd, kka[k + 1], y); if (SK) y = fmaf(vt, kx[k + 1], y); s[k + 1] = y; o1 = fmaf(y, r[k + 1], o1);
	v_fmac_f32_dpp v76, v100, v142 row_newbcast:1 row_mask:0xf bank_mask:0xf
	v_fmac_f32_dpp v77, v101, v142 row_newbcast:1 row_mask:0xf bank_mask:0xf
	v_fmac_f32_dpp v74, v102, v142 row_newbcast:1 row_mask:0xf bank_mask:0xf
	v_fmac_f32_dpp v75, v103, v142 row_newbcast:1 row_mask:0xf bank_mask:0xf
	v_fmac_f32_dpp v76, v104, v132 row_newbcast:1 row_mask:0xf bank_mask:0xf
	v_fmac_f32_dpp v77, v105, v132 row_newbcast:1 row_mask:0xf bank_mask:0xf
	v_fmac_f32_dpp v74, v106, v132 row_newbcast:1 row_mask:0xf bank_mask:0xf
	v_fmac_f32_dpp v75, v107, v132 row_newbcast:1 row_mask:0xf bank_mask:0xf
	v_fmac_f32_dpp v138, v108, v76 row_newbcast:1 row_mask:0xf bank_mask:0xf
	v_fmac_f32_dpp v139, v109, v77 row_newbcast:1 row_mask:0xf bank_mask:0xf
	v_fmac_f32_dpp v140, v110, v74 row_newbcast:1 row_mask:0xf bank_mask:0xf
	v_fmac_f32_dpp v141, v111, v75 row_newbcast:1 row_mask:0xf bank_mask:0xf
	v_mul_f32_dpp v72, v96, v72 row_newbcast:2 row_mask:0xf bank_mask:0xf
	v_mul_f32_dpp v73, v97, v73 row_newbcast:2 row_mask:0xf bank_mask:0xf
	v_mul_f32_dpp v66, v98, v66 row_newbcast:2 row_mask:0xf bank_mask:0xf
	v_mul_f32_dpp v67, v99, v67 row_newbcast:2 row_mask:0xf bank_mask:0xf
	v_fmac_f32_dpp v72, v100, v142 row_newbcast:2 row_mask:0xf bank_mask:0xf
	v_fmac_f32_dpp v73, v101, v142 row_newbcast:2 row_mask:0xf bank_mask:0xf
	v_fmac_f32_dpp v66, v102, v142 row_newbcast:2 row_mask:0xf bank_mask:0xf
	v_fmac_f32_dpp v67, v103, v142 row_newbcast:2 row_mask:0xf bank_mask:0xf
	v_fmac_f32_dpp v72, v104, v132 row_newbcast:2 row_mask:0xf bank_mask:0xf
	v_fmac_f32_dpp v73, v105, v132 row_newbcast:2 row_mask:0xf bank_mask:0xf
	v_fmac_f32_dpp v66, v106, v132 row_newbcast:2 row_mask:0xf bank_mask:0xf
	v_fmac_f32_dpp v67, v107, v132 row_newbcast:2 row_mask:0xf bank_mask:0xf
	v_fmac_f32_dpp v138, v108, v72 row_newbcast:2 row_mask:0xf bank_mask:0xf
	v_fmac_f32_dpp v139, v109, v73 row_newbcast:2 row_mask:0xf bank_mask:0xf
	v_fmac_f32_dpp v140, v110, v66 row_newbcast:2 row_mask:0xf bank_mask:0xf
	v_fmac_f32_dpp v141, v111, v67 row_newbcast:2 row_mask:0xf bank_mask:0xf
	v_mul_f32_dpp v64, v96, v64 row_newbcast:3 row_mask:0xf bank_mask:0xf
	v_mul_f32_dpp v65, v97, v65 row_newbcast:3 row_mask:0xf bank_mask:0xf
	v_mul_f32_dpp v62, v98, v62 row_newbcast:3 row_mask:0xf bank_mask:0xf
	v_mul_f32_dpp v63, v99, v63 row_newbcast:3 row_mask:0xf bank_mask:0xf
	v_fmac_f32_dpp v64, v100, v142 row_newbcast:3 row_mask:0xf bank_mask:0xf
	v_fmac_f32_dpp v65, v101, v142 row_newbcast:3 row_mask:0xf bank_mask:0xf
	v_fmac_f32_dpp v62, v102, v142 row_newbcast:3 row_mask:0xf bank_mask:0xf
	v_fmac_f32_dpp v63, v103, v142 row_newbcast:3 row_mask:0xf bank_mask:0xf
	v_fmac_f32_dpp v64, v104, v132 row_newbcast:3 row_mask:0xf bank_mask:0xf
	v_fmac_f32_dpp v65, v105, v132 row_newbcast:3 row_mask:0xf bank_mask:0xf
	v_fmac_f32_dpp v62, v106, v132 row_newbcast:3 row_mask:0xf bank_mask:0xf
	v_fmac_f32_dpp v63, v107, v132 row_newbcast:3 row_mask:0xf bank_mask:0xf
	v_fmac_f32_dpp v138, v108, v64 row_newbcast:3 row_mask:0xf bank_mask:0xf
	v_fmac_f32_dpp v139, v109, v65 row_newbcast:3 row_mask:0xf bank_mask:0xf
	v_fmac_f32_dpp v140, v110, v62 row_newbcast:3 row_mask:0xf bank_mask:0xf
	v_fmac_f32_dpp v141, v111, v63 row_newbcast:3 row_mask:0xf bank_mask:0xf
	v_mul_f32_dpp v60, v96, v60 row_newbcast:4 row_mask:0xf bank_mask:0xf
	v_mul_f32_dpp v61, v97, v61 row_newbcast:4 row_mask:0xf bank_mask:0xf
	v_mul_f32_dpp v58, v98, v58 row_newbcast:4 row_mask:0xf bank_mask:0xf
	v_mul_f32_dpp v59, v99, v59 row_newbcast:4 row_mask:0xf bank_mask:0xf
	v_fmac_f32_dpp v60, v100, v142 row_newbcast:4 row_mask:0xf bank_mask:0xf
	v_fmac_f32_dpp v61, v101, v142 row_newbcast:4 row_mask:0xf bank_mask:0xf
	v_fmac_f32_dpp v58, v102, v142 row_newbcast:4 row_mask:0xf bank_mask:0xf
	v_fmac_f32_dpp v59, v103, v142 row_newbcast:4 row_mask:0xf bank_mask:0xf
	v_fmac_f32_dpp v60, v104, v132 row_newbcast:4 row_mask:0xf bank_mask:0xf
	v_fmac_f32_dpp v61, v105, v132 row_newbcast:4 row_mask:0xf bank_mask:0xf
	v_fmac_f32_dpp v58, v106, v132 row_newbcast:4 row_mask:0xf bank_mask:0xf
	v_fmac_f32_dpp v59, v107, v132 row_newbcast:4 row_mask:0xf bank_mask:0xf
	v_fmac_f32_dpp v138, v108, v60 row_newbcast:4 row_mask:0xf bank_mask:0xf
	v_fmac_f32_dpp v139, v109, v61 row_newbcast:4 row_mask:0xf bank_mask:0xf
	v_fmac_f32_dpp v140, v110, v58 row_newbcast:4 row_mask:0xf bank_mask:0xf
	v_fmac_f32_dpp v141, v111, v59 row_newbcast:4 row_mask:0xf bank_mask:0xf
	v_mul_f32_dpp v56, v96, v56 row_newbcast:5 row_mask:0xf bank_mask:0xf
	v_mul_f32_dpp v57, v97, v57 row_newbcast:5 row_mask:0xf bank_mask:0xf
	v_mul_f32_dpp v54, v98, v54 row_newbcast:5 row_mask:0xf bank_mask:0xf
	v_mul_f32_dpp v55, v99, v55 row_newbcast:5 row_mask:0xf bank_mask:0xf
	v_fmac_f32_dpp v56, v100, v142 row_newbcast:5 row_mask:0xf bank_mask:0xf
	v_fmac_f32_dpp v57, v101, v142 row_newbcast:5 row_mask:0xf bank_mask:0xf
	v_fmac_f32_dpp v54, v102, v142 row_newbcast:5 row_mask:0xf bank_mask:0xf
	v_fmac_f32_dpp v55, v103, v142 row_newbcast:5 row_mask:0xf bank_mask:0xf
	v_fmac_f32_dpp v56, v104, v132 row_newbcast:5 row_mask:0xf bank_mask:0xf
	v_fmac_f32_dpp v57, v105, v132 row_newbcast:5 row_mask:0xf bank_mask:0xf
	v_fmac_f32_dpp v54, v106, v132 row_newbcast:5 row_mask:0xf bank_mask:0xf
	v_fmac_f32_dpp v55, v107, v132 row_newbcast:5 row_mask:0xf bank_mask:0xf
	v_fmac_f32_dpp v138, v108, v56 row_newbcast:5 row_mask:0xf bank_mask:0xf
	v_fmac_f32_dpp v139, v109, v57 row_newbcast:5 row_mask:0xf bank_mask:0xf
	v_fmac_f32_dpp v140, v110, v54 row_newbcast:5 row_mask:0xf bank_mask:0xf
	v_fmac_f32_dpp v141, v111, v55 row_newbcast:5 row_mask:0xf bank_mask:0xf
	v_mul_f32_dpp v50, v96, v50 row_newbcast:6 row_mask:0xf bank_mask:0xf
; template <bool SK>
; __device__ __forceinline__ void scan_task(const float* R, const float* W, const float* KX, const float* KK, const float* KKA, const float* V, float* OUT, float* STT, const float* S0, float* SOUT, int nstep, int lane) {
;     ...
;         float o0 = 0.f, o1 = 0.f;
; #pragma unroll
;         for (int k = 0; k < 64; k += 2) {
;             float x = s[k] * w[k]; x = fmaf(nd, kka[k], x); if (SK) x = fmaf(vt, kx[k], x); s[k] = x; o0 = fmaf(x, r[k], o0);
;             float y = s[k + 1] * w[k + 1]; y = fmaf(nd, kka[k + 1], y); if (SK) y = fmaf(vt, kx[k + 1], y); s[k + 1] = y; o1 = fmaf(y, r[k + 1], o1);
	v_mul_f32_dpp v51, v97, v51 row_newbcast:6 row_mask:0xf bank_mask:0xf
	v_mul_f32_dpp v48, v98, v48 row_newbcast:6 row_mask:0xf bank_mask:0xf
	v_mul_f32_dpp v49, v99, v49 row_newbcast:6 row_mask:0xf bank_mask:0xf
	v_fmac_f32_dpp v50, v100, v142 row_newbcast:6 row_mask:0xf bank_mask:0xf
	v_fmac_f32_dpp v51, v101, v142 row_newbcast:6 row_mask:0xf bank_mask:0xf
	v_fmac_f32_dpp v48, v102, v142 row_newbcast:6 row_mask:0xf bank_mask:0xf
	v_fmac_f32_dpp v49, v103, v142 row_newbcast:6 row_mask:0xf bank_mask:0xf
	v_fmac_f32_dpp v50, v104, v132 row_newbcast:6 row_mask:0xf bank_mask:0xf
	v_fmac_f32_dpp v51, v105, v132 row_newbcast:6 row_mask:0xf bank_mask:0xf
	v_fmac_f32_dpp v48, v106, v132 row_newbcast:6 row_mask:0xf bank_mask:0xf
	v_fmac_f32_dpp v49, v107, v132 row_newbcast:6 row_mask:0xf bank_mask:0xf
	v_fmac_f32_dpp v138, v108, v50 row_newbcast:6 row_mask:0xf bank_mask:0xf
	v_fmac_f32_dpp v139, v109, v51 row_newbcast:6 row_mask:0xf bank_mask:0xf
	v_fmac_f32_dpp v140, v110, v48 row_newbcast:6 row_mask:0xf bank_mask:0xf
	v_fmac_f32_dpp v141, v111, v49 row_newbcast:6 row_mask:0xf bank_mask:0xf
	v_mul_f32_dpp v46, v96, v46 row_newbcast:7 row_mask:0xf bank_mask:0xf
	v_mul_f32_dpp v47, v97, v47 row_newbcast:7 row_mask:0xf bank_mask:0xf
	v_mul_f32_dpp v44, v98, v44 row_newbcast:7 row_mask:0xf bank_mask:0xf
	v_mul_f32_dpp v45, v99, v45 row_newbcast:7 row_mask:0xf bank_mask:0xf
	v_fmac_f32_dpp v46, v100, v142 row_newbcast:7 row_mask:0xf bank_mask:0xf
	v_fmac_f32_dpp v47, v101, v142 row_newbcast:7 row_mask:0xf bank_mask:0xf
	v_fmac_f32_dpp v44, v102, v142 row_newbcast:7 row_mask:0xf bank_mask:0xf
	v_fmac_f32_dpp v45, v103, v142 row_newbcast:7 row_mask:0xf bank_mask:0xf
	v_fmac_f32_dpp v46, v104, v132 row_newbcast:7 row_mask:0xf bank_mask:0xf
	v_fmac_f32_dpp v47, v105, v132 row_newbcast:7 row_mask:0xf bank_mask:0xf
	v_fmac_f32_dpp v44, v106, v132 row_newbcast:7 row_mask:0xf bank_mask:0xf
	v_fmac_f32_dpp v45, v107, v132 row_newbcast:7 row_mask:0xf bank_mask:0xf
	v_fmac_f32_dpp v138, v108, v46 row_newbcast:7 row_mask:0xf bank_mask:0xf
	v_fmac_f32_dpp v139, v109, v47 row_newbcast:7 row_mask:0xf bank_mask:0xf
	v_fmac_f32_dpp v140, v110, v44 row_newbcast:7 row_mask:0xf bank_mask:0xf
	v_fmac_f32_dpp v141, v111, v45 row_newbcast:7 row_mask:0xf bank_mask:0xf
	v_mul_f32_dpp v42, v96, v42 row_newbcast:8 row_mask:0xf bank_mask:0xf
	v_mul_f32_dpp v43, v97, v43 row_newbcast:8 row_mask:0xf bank_mask:0xf
	v_mul_f32_dpp v40, v98, v40 row_newbcast:8 row_mask:0xf bank_mask:0xf
	v_mul_f32_dpp v41, v99, v41 row_newbcast:8 row_mask:0xf bank_mask:0xf
	v_fmac_f32_dpp v42, v100, v142 row_newbcast:8 row_mask:0xf bank_mask:0xf
	v_fmac_f32_dpp v43, v101, v142 row_newbcast:8 row_mask:0xf bank_mask:0xf
	v_fmac_f32_dpp v40, v102, v142 row_newbcast:8 row_mask:0xf bank_mask:0xf
	v_fmac_f32_dpp v41, v103, v142 row_newbcast:8 row_mask:0xf bank_mask:0xf
	v_fmac_f32_dpp v42, v104, v132 row_newbcast:8 row_mask:0xf bank_mask:0xf
	v_fmac_f32_dpp v43, v105, v132 row_newbcast:8 row_mask:0xf bank_mask:0xf
	v_fmac_f32_dpp v40, v106, v132 row_newbcast:8 row_mask:0xf bank_mask:0xf
	v_fmac_f32_dpp v41, v107, v132 row_newbcast:8 row_mask:0xf bank_mask:0xf
	v_fmac_f32_dpp v138, v108, v42 row_newbcast:8 row_mask:0xf bank_mask:0xf
	v_fmac_f32_dpp v139, v109, v43 row_newbcast:8 row_mask:0xf bank_mask:0xf
	v_fmac_f32_dpp v140, v110, v40 row_newbcast:8 row_mask:0xf bank_mask:0xf
	v_fmac_f32_dpp v141, v111, v41 row_newbcast:8 row_mask:0xf bank_mask:0xf
	v_mul_f32_dpp v38, v96, v38 row_newbcast:9 row_mask:0xf bank_mask:0xf
	v_mul_f32_dpp v39, v97, v39 row_newbcast:9 row_mask:0xf bank_mask:0xf
	v_mul_f32_dpp v36, v98, v36 row_newbcast:9 row_mask:0xf bank_mask:0xf
	v_mul_f32_dpp v37, v99, v37 row_newbcast:9 row_mask:0xf bank_mask:0xf
	v_fmac_f32_dpp v38, v100, v142 row_newbcast:9 row_mask:0xf bank_mask:0xf
	v_fmac_f32_dpp v39, v101, v142 row_newbcast:9 row_mask:0xf bank_mask:0xf
	v_fmac_f32_dpp v36, v102, v142 row_newbcast:9 row_mask:0xf bank_mask:0xf
	v_fmac_f32_dpp v37, v103, v142 row_newbcast:9 row_mask:0xf bank_mask:0xf
	v_fmac_f32_dpp v38, v104, v132 row_newbcast:9 row_mask:0xf bank_mask:0xf
	v_fmac_f32_dpp v39, v105, v132 row_newbcast:9 row_mask:0xf bank_mask:0xf
	v_fmac_f32_dpp v36, v106, v132 row_newbcast:9 row_mask:0xf bank_mask:0xf
	v_fmac_f32_dpp v37, v107, v132 row_newbcast:9 row_mask:0xf bank_mask:0xf
	v_fmac_f32_dpp v138, v108, v38 row_newbcast:9 row_mask:0xf bank_mask:0xf
	v_fmac_f32_dpp v139, v109, v39 row_newbcast:9 row_mask:0xf bank_mask:0xf
	v_fmac_f32_dpp v140, v110, v36 row_newbcast:9 row_mask:0xf bank_mask:0xf
	v_fmac_f32_dpp v141, v111, v37 row_newbcast:9 row_mask:0xf bank_mask:0xf
	v_mul_f32_dpp v32, v96, v32 row_newbcast:10 row_mask:0xf bank_mask:0xf
	v_mul_f32_dpp v33, v97, v33 row_newbcast:10 row_mask:0xf bank_mask:0xf
	v_mul_f32_dpp v30, v98, v30 row_newbcast:10 row_mask:0xf bank_mask:0xf
	v_mul_f32_dpp v31, v99, v31 row_newbcast:10 row_mask:0xf bank_mask:0xf
	v_fmac_f32_dpp v32, v100, v142 row_newbcast:10 row_mask:0xf bank_mask:0xf
	v_fmac_f32_dpp v33, v101, v142 row_newbcast:10 row_mask:0xf bank_mask:0xf
	v_fmac_f32_dpp v30, v102, v142 row_newbcast:10 row_mask:0xf bank_mask:0xf
	v_fmac_f32_dpp v31, v103, v142 row_newbcast:10 row_mask:0xf bank_mask:0xf
	v_fmac_f32_dpp v32, v104, v132 row_newbcast:10 row_mask:0xf bank_mask:0xf
	v_fmac_f32_dpp v33, v105, v132 row_newbcast:10 row_mask:0xf bank_mask:0xf
	v_fmac_f32_dpp v30, v106, v132 row_newbcast:10 row_mask:0xf bank_mask:0xf
	v_fmac_f32_dpp v31, v107, v132 row_newbcast:10 row_mask:0xf bank_mask:0xf
	v_fmac_f32_dpp v138, v108, v32 row_newbcast:10 row_mask:0xf bank_mask:0xf
	v_fmac_f32_dpp v139, v109, v33 row_newbcast:10 row_mask:0xf bank_mask:0xf
; template <bool SK>
; __device__ __forceinline__ void scan_task(const float* R, const float* W, const float* KX, const float* KK, const float* KKA, const float* V, float* OUT, float* STT, const float* S0, float* SOUT, int nstep, int lane) {
;     ...
;         { const int tp = (t + 2 < nstep) ? t + 2 : t; const size_t po = (size_t)tp * BW + lane;
;           pf0 = KK[po]; pf1 = W[po]; pf2 = KKA[po]; pf3 = KX[po]; pf4 = R[po]; }
;         cfloat* kk = (cfloat*)(KK + (size_t)t * BW); cfloat* w = (cfloat*)(W + (size_t)t * BW); cfloat* kka = (cfloat*)(KKA + (size_t)t * BW);
;         cfloat* kx = (cfloat*)(KX + (size_t)t * BW); cfloat* r = (cfloat*)(R + (size_t)t * BW);
;         float d0 = 0.f, d1 = 0.f;
; #pragma unroll
;         for (int k = 0; k < 64; k += 2) { d0 = fmaf(s[k], kk[k], d0); d1 = fmaf(s[k + 1], kk[k + 1], d1); }
;     ...
;         for (int k = 0; k < 64; k += 2) {
;             float x = s[k] * w[k]; x = fmaf(nd, kka[k], x); if (SK) x = fmaf(vt, kx[k], x); s[k] = x; o0 = fmaf(x, r[k], o0);
;             float y = s[k + 1] * w[k + 1]; y = fmaf(nd, kka[k + 1], y); if (SK) y = fmaf(vt, kx[k + 1], y); s[k + 1] = y; o1 = fmaf(y, r[k + 1], o1);
;         }
;         OUT[(size_t)t * BW + lane] = o0 + o1;
	v_fmac_f32_dpp v140, v110, v30 row_newbcast:10 row_mask:0xf bank_mask:0xf
	v_fmac_f32_dpp v141, v111, v31 row_newbcast:10 row_mask:0xf bank_mask:0xf
	v_mul_f32_dpp v28, v96, v28 row_newbcast:11 row_mask:0xf bank_mask:0xf
	v_mul_f32_dpp v29, v97, v29 row_newbcast:11 row_mask:0xf bank_mask:0xf
	v_mul_f32_dpp v26, v98, v26 row_newbcast:11 row_mask:0xf bank_mask:0xf
	v_mul_f32_dpp v27, v99, v27 row_newbcast:11 row_mask:0xf bank_mask:0xf
	v_fmac_f32_dpp v28, v100, v142 row_newbcast:11 row_mask:0xf bank_mask:0xf
	v_fmac_f32_dpp v29, v101, v142 row_newbcast:11 row_mask:0xf bank_mask:0xf
	v_fmac_f32_dpp v26, v102, v142 row_newbcast:11 row_mask:0xf bank_mask:0xf
	v_fmac_f32_dpp v27, v103, v142 row_newbcast:11 row_mask:0xf bank_mask:0xf
	v_fmac_f32_dpp v28, v104, v132 row_newbcast:11 row_mask:0xf bank_mask:0xf
	v_fmac_f32_dpp v29, v105, v132 row_newbcast:11 row_mask:0xf bank_mask:0xf
	v_fmac_f32_dpp v26, v106, v132 row_newbcast:11 row_mask:0xf bank_mask:0xf
	v_fmac_f32_dpp v27, v107, v132 row_newbcast:11 row_mask:0xf bank_mask:0xf
	v_fmac_f32_dpp v138, v108, v28 row_newbcast:11 row_mask:0xf bank_mask:0xf
	v_fmac_f32_dpp v139, v109, v29 row_newbcast:11 row_mask:0xf bank_mask:0xf
	v_fmac_f32_dpp v140, v110, v26 row_newbcast:11 row_mask:0xf bank_mask:0xf
	v_fmac_f32_dpp v141, v111, v27 row_newbcast:11 row_mask:0xf bank_mask:0xf
	v_mul_f32_dpp v24, v96, v24 row_newbcast:12 row_mask:0xf bank_mask:0xf
	v_mul_f32_dpp v25, v97, v25 row_newbcast:12 row_mask:0xf bank_mask:0xf
	v_mul_f32_dpp v22, v98, v22 row_newbcast:12 row_mask:0xf bank_mask:0xf
	v_mul_f32_dpp v23, v99, v23 row_newbcast:12 row_mask:0xf bank_mask:0xf
	v_fmac_f32_dpp v24, v100, v142 row_newbcast:12 row_mask:0xf bank_mask:0xf
	v_fmac_f32_dpp v25, v101, v142 row_newbcast:12 row_mask:0xf bank_mask:0xf
	v_fmac_f32_dpp v22, v102, v142 row_newbcast:12 row_mask:0xf bank_mask:0xf
	v_fmac_f32_dpp v23, v103, v142 row_newbcast:12 row_mask:0xf bank_mask:0xf
	v_fmac_f32_dpp v24, v104, v132 row_newbcast:12 row_mask:0xf bank_mask:0xf
	v_fmac_f32_dpp v25, v105, v132 row_newbcast:12 row_mask:0xf bank_mask:0xf
	v_fmac_f32_dpp v22, v106, v132 row_newbcast:12 row_mask:0xf bank_mask:0xf
	v_fmac_f32_dpp v23, v107, v132 row_newbcast:12 row_mask:0xf bank_mask:0xf
	v_fmac_f32_dpp v138, v108, v24 row_newbcast:12 row_mask:0xf bank_mask:0xf
	v_fmac_f32_dpp v139, v109, v25 row_newbcast:12 row_mask:0xf bank_mask:0xf
	v_fmac_f32_dpp v140, v110, v22 row_newbcast:12 row_mask:0xf bank_mask:0xf
	v_fmac_f32_dpp v141, v111, v23 row_newbcast:12 row_mask:0xf bank_mask:0xf
	v_mul_f32_dpp v20, v96, v20 row_newbcast:13 row_mask:0xf bank_mask:0xf
	v_mul_f32_dpp v21, v97, v21 row_newbcast:13 row_mask:0xf bank_mask:0xf
	v_mul_f32_dpp v18, v98, v18 row_newbcast:13 row_mask:0xf bank_mask:0xf
	v_mul_f32_dpp v19, v99, v19 row_newbcast:13 row_mask:0xf bank_mask:0xf
	v_fmac_f32_dpp v20, v100, v142 row_newbcast:13 row_mask:0xf bank_mask:0xf
	v_fmac_f32_dpp v21, v101, v142 row_newbcast:13 row_mask:0xf bank_mask:0xf
	v_fmac_f32_dpp v18, v102, v142 row_newbcast:13 row_mask:0xf bank_mask:0xf
	v_fmac_f32_dpp v19, v103, v142 row_newbcast:13 row_mask:0xf bank_mask:0xf
	v_fmac_f32_dpp v20, v104, v132 row_newbcast:13 row_mask:0xf bank_mask:0xf
	v_fmac_f32_dpp v21, v105, v132 row_newbcast:13 row_mask:0xf bank_mask:0xf
	v_fmac_f32_dpp v18, v106, v132 row_newbcast:13 row_mask:0xf bank_mask:0xf
	v_fmac_f32_dpp v19, v107, v132 row_newbcast:13 row_mask:0xf bank_mask:0xf
	v_fmac_f32_dpp v138, v108, v20 row_newbcast:13 row_mask:0xf bank_mask:0xf
	v_fmac_f32_dpp v139, v109, v21 row_newbcast:13 row_mask:0xf bank_mask:0xf
	v_fmac_f32_dpp v140, v110, v18 row_newbcast:13 row_mask:0xf bank_mask:0xf
	v_fmac_f32_dpp v141, v111, v19 row_newbcast:13 row_mask:0xf bank_mask:0xf
	v_mul_f32_dpp v16, v96, v16 row_newbcast:14 row_mask:0xf bank_mask:0xf
	v_mul_f32_dpp v17, v97, v17 row_newbcast:14 row_mask:0xf bank_mask:0xf
	v_mul_f32_dpp v14, v98, v14 row_newbcast:14 row_mask:0xf bank_mask:0xf
	v_mul_f32_dpp v15, v99, v15 row_newbcast:14 row_mask:0xf bank_mask:0xf
	v_fmac_f32_dpp v16, v100, v142 row_newbcast:14 row_mask:0xf bank_mask:0xf
	v_fmac_f32_dpp v17, v101, v142 row_newbcast:14 row_mask:0xf bank_mask:0xf
	v_fmac_f32_dpp v14, v102, v142 row_newbcast:14 row_mask:0xf bank_mask:0xf
	v_fmac_f32_dpp v15, v103, v142 row_newbcast:14 row_mask:0xf bank_mask:0xf
	v_fmac_f32_dpp v16, v104, v132 row_newbcast:14 row_mask:0xf bank_mask:0xf
	v_fmac_f32_dpp v17, v105, v132 row_newbcast:14 row_mask:0xf bank_mask:0xf
	v_fmac_f32_dpp v14, v106, v132 row_newbcast:14 row_mask:0xf bank_mask:0xf
	v_fmac_f32_dpp v15, v107, v132 row_newbcast:14 row_mask:0xf bank_mask:0xf
	v_fmac_f32_dpp v138, v108, v16 row_newbcast:14 row_mask:0xf bank_mask:0xf
	v_fmac_f32_dpp v139, v109, v17 row_newbcast:14 row_mask:0xf bank_mask:0xf
	v_fmac_f32_dpp v140, v110, v14 row_newbcast:14 row_mask:0xf bank_mask:0xf
	v_fmac_f32_dpp v141, v111, v15 row_newbcast:14 row_mask:0xf bank_mask:0xf
	v_mul_f32_dpp v12, v96, v12 row_newbcast:15 row_mask:0xf bank_mask:0xf
	v_mul_f32_dpp v13, v97, v13 row_newbcast:15 row_mask:0xf bank_mask:0xf
	v_mul_f32_dpp v82, v98, v82 row_newbcast:15 row_mask:0xf bank_mask:0xf
	v_mul_f32_dpp v83, v99, v83 row_newbcast:15 row_mask:0xf bank_mask:0xf
	v_fmac_f32_dpp v12, v100, v142 row_newbcast:15 row_mask:0xf bank_mask:0xf
	v_fmac_f32_dpp v13, v101, v142 row_newbcast:15 row_mask:0xf bank_mask:0xf
	v_fmac_f32_dpp v82, v102, v142 row_newbcast:15 row_mask:0xf bank_mask:0xf
	v_fmac_f32_dpp v83, v103, v142 row_newbcast:15 row_mask:0xf bank_mask:0xf
	v_fmac_f32_dpp v12, v104, v132 row_newbcast:15 row_mask:0xf bank_mask:0xf
	v_fmac_f32_dpp v13, v105, v132 row_newbcast:15 row_mask:0xf bank_mask:0xf
	v_fmac_f32_dpp v82, v106, v132 row_newbcast:15 row_mask:0xf bank_mask:0xf
	v_fmac_f32_dpp v83, v107, v132 row_newbcast:15 row_mask:0xf bank_mask:0xf
	v_fmac_f32_dpp v138, v108, v12 row_newbcast:15 row_mask:0xf bank_mask:0xf
	v_fmac_f32_dpp v139, v109, v13 row_newbcast:15 row_mask:0xf bank_mask:0xf
	v_fmac_f32_dpp v140, v110, v82 row_newbcast:15 row_mask:0xf bank_mask:0xf
	v_fmac_f32_dpp v141, v111, v83 row_newbcast:15 row_mask:0xf bank_mask:0xf
	global_load_dwordx4 v[96:99], v143, s[90:91]
	global_load_dwordx4 v[100:103], v143, s[94:95]
	global_load_dwordx4 v[104:107], v143, s[92:93]
	global_load_dwordx4 v[108:111], v143, s[88:89]
	global_load_dword v132, v144, s[0:1]
	v_add_f32_e32 v138, v138, v140
	v_add_f32_e32 v139, v139, v141
	v_add_f32_e32 v138, v138, v139
	global_store_dword v144, v138, s[2:3]
	s_waitcnt vmcnt(8) lgkmcnt(0)
; template <bool SK>
; __device__ __forceinline__ void scan_task(const float* R, const float* W, const float* KX, const float* KK, const float* KKA, const float* V, float* OUT, float* STT, const float* S0, float* SOUT, int nstep, int lane) {
;     ...
;         { const int tp = (t + 2 < nstep) ? t + 2 : t; const size_t po = (size_t)tp * BW + lane;
;           pf0 = KK[po]; pf1 = W[po]; pf2 = KKA[po]; pf3 = KX[po]; pf4 = R[po]; }
;         cfloat* kk = (cfloat*)(KK + (size_t)t * BW); cfloat* w = (cfloat*)(W + (size_t)t * BW); cfloat* kka = (cfloat*)(KKA + (size_t)t * BW);
;         cfloat* kx = (cfloat*)(KX + (size_t)t * BW); cfloat* r = (cfloat*)(R + (size_t)t * BW);
;         float d0 = 0.f, d1 = 0.f;
; #pragma unroll
;         for (int k = 0; k < 64; k += 2) { d0 = fmaf(s[k], kk[k], d0); d1 = fmaf(s[k + 1], kk[k + 1], d1); }
;         const float nd = -(d0 + d1);
;         const float vt = SK ? V[(size_t)t * BW + lane] : 0.f;
;         float o0 = 0.f, o1 = 0.f;
; #pragma unroll
;         for (int k = 0; k < 64; k += 2) {
;             float x = s[k] * w[k]; x = fmaf(nd, kka[k], x); if (SK) x = fmaf(vt, kx[k], x); s[k] = x; o0 = fmaf(x, r[k], o0);
	v_pk_mul_f32 v[134:135], v[80:81], s[4:5]
	v_pk_mul_f32 v[136:137], v[78:79], s[6:7]
	v_pk_fma_f32 v[134:135], v[76:77], s[8:9], v[134:135]
	v_pk_fma_f32 v[136:137], v[74:75], s[10:11], v[136:137]
	v_pk_fma_f32 v[134:135], v[72:73], s[12:13], v[134:135]
	v_pk_fma_f32 v[136:137], v[66:67], s[14:15], v[136:137]
	v_pk_fma_f32 v[134:135], v[64:65], s[16:17], v[134:135]
	v_pk_fma_f32 v[136:137], v[62:63], s[18:19], v[136:137]
	v_pk_fma_f32 v[134:135], v[60:61], s[40:41], v[134:135]
	v_pk_fma_f32 v[136:137], v[58:59], s[42:43], v[136:137]
	v_pk_fma_f32 v[134:135], v[56:57], s[44:45], v[134:135]
	v_pk_fma_f32 v[136:137], v[54:55], s[46:47], v[136:137]
	v_pk_fma_f32 v[134:135], v[50:51], s[48:49], v[134:135]
	v_pk_fma_f32 v[136:137], v[48:49], s[50:51], v[136:137]
	v_pk_fma_f32 v[134:135], v[46:47], s[52:53], v[134:135]
	v_pk_fma_f32 v[136:137], v[44:45], s[54:55], v[136:137]
	v_pk_fma_f32 v[134:135], v[42:43], s[56:57], v[134:135]
	v_pk_fma_f32 v[136:137], v[40:41], s[58:59], v[136:137]
	v_pk_fma_f32 v[134:135], v[38:39], s[60:61], v[134:135]
	v_pk_fma_f32 v[136:137], v[36:37], s[62:63], v[136:137]
	v_pk_fma_f32 v[134:135], v[32:33], s[64:65], v[134:135]
	v_pk_fma_f32 v[136:137], v[30:31], s[66:67], v[136:137]
	v_pk_fma_f32 v[134:135], v[28:29], s[68:69], v[134:135]
	v_pk_fma_f32 v[136:137], v[26:27], s[70:71], v[136:137]
	s_nop 0
	v_fmac_f32_dpp v134, v112, v24 row_newbcast:12 row_mask:0xf bank_mask:0xf
	v_fmac_f32_dpp v135, v113, v25 row_newbcast:12 row_mask:0xf bank_mask:0xf
	v_fmac_f32_dpp v136, v114, v22 row_newbcast:12 row_mask:0xf bank_mask:0xf
	v_fmac_f32_dpp v137, v115, v23 row_newbcast:12 row_mask:0xf bank_mask:0xf
	v_fmac_f32_dpp v134, v112, v20 row_newbcast:13 row_mask:0xf bank_mask:0xf
	v_fmac_f32_dpp v135, v113, v21 row_newbcast:13 row_mask:0xf bank_mask:0xf
	v_fmac_f32_dpp v136, v114, v18 row_newbcast:13 row_mask:0xf bank_mask:0xf
	v_fmac_f32_dpp v137, v115, v19 row_newbcast:13 row_mask:0xf bank_mask:0xf
	v_fmac_f32_dpp v134, v112, v16 row_newbcast:14 row_mask:0xf bank_mask:0xf
	v_fmac_f32_dpp v135, v113, v17 row_newbcast:14 row_mask:0xf bank_mask:0xf
	v_fmac_f32_dpp v136, v114, v14 row_newbcast:14 row_mask:0xf bank_mask:0xf
	v_fmac_f32_dpp v137, v115, v15 row_newbcast:14 row_mask:0xf bank_mask:0xf
	v_fmac_f32_dpp v134, v112, v12 row_newbcast:15 row_mask:0xf bank_mask:0xf
	v_fmac_f32_dpp v135, v113, v13 row_newbcast:15 row_mask:0xf bank_mask:0xf
	v_fmac_f32_dpp v136, v114, v82 row_newbcast:15 row_mask:0xf bank_mask:0xf
	v_fmac_f32_dpp v137, v115, v83 row_newbcast:15 row_mask:0xf bank_mask:0xf
	global_load_dwordx4 v[112:115], v143, s[96:97] offset:2048
	s_add_u32 s34, s34, 0x800
	s_addc_u32 s35, s35, 0
	s_nop 1
	s_load_dwordx16 s[4:19], s[34:35], 0x0
	s_load_dwordx16 s[40:55], s[34:35], 0x40
	s_load_dwordx16 s[56:71], s[34:35], 0x80
	v_add_f32_e32 v134, v134, v136
	v_add_f32_e32 v135, v135, v137
	v_add_f32_e32 v142, v134, v135
	v_xor_b32_e32 v142, 0x80000000, v142
	v_mul_f32_dpp v80, v116, v80 row_newbcast:0 row_mask:0xf bank_mask:0xf
	v_mul_f32_dpp v81, v117, v81 row_newbcast:0 row_mask:0xf bank_mask:0xf
	v_mul_f32_dpp v78, v118, v78 row_newbcast:0 row_mask:0xf bank_mask:0xf
	v_mul_f32_dpp v79, v119, v79 row_newbcast:0 row_mask:0xf bank_mask:0xf
	v_fmac_f32_dpp v80, v120, v142 row_newbcast:0 row_mask:0xf bank_mask:0xf
	v_fmac_f32_dpp v81, v121, v142 row_newbcast:0 row_mask:0xf bank_mask:0xf
	v_fmac_f32_dpp v78, v122, v142 row_newbcast:0 row_mask:0xf bank_mask:0xf
	v_fmac_f32_dpp v79, v123, v142 row_newbcast:0 row_mask:0xf bank_mask:0xf
	v_fmac_f32_dpp v80, v124, v133 row_newbcast:0 row_mask:0xf bank_mask:0xf
	v_fmac_f32_dpp v81, v125, v133 row_newbcast:0 row_mask:0xf bank_mask:0xf
	v_fmac_f32_dpp v78, v126, v133 row_newbcast:0 row_mask:0xf bank_mask:0xf
	v_fmac_f32_dpp v79, v127, v133 row_newbcast:0 row_mask:0xf bank_mask:0xf
	v_mul_f32_dpp v138, v128, v80 row_newbcast:0 row_mask:0xf bank_mask:0xf
	v_mul_f32_dpp v139, v129, v81 row_newbcast:0 row_mask:0xf bank_mask:0xf
	v_mul_f32_dpp v140, v130, v78 row_newbcast:0 row_mask:0xf bank_mask:0xf
	v_mul_f32_dpp v141, v131, v79 row_newbcast:0 row_mask:0xf bank_mask:0xf
	v_mul_f32_dpp v76, v116, v76 row_newbcast:1 row_mask:0xf bank_mask:0xf
	v_mul_f32_dpp v77, v117, v77 row_newbcast:1 row_mask:0xf bank_mask:0xf
	v_mul_f32_dpp v74, v118, v74 row_newbcast:1 row_mask:0xf bank_mask:0xf
	v_mul_f32_dpp v75, v119, v75 row_newbcast:1 row_mask:0xf bank_mask:0xf
	v_fmac_f32_dpp v76, v120, v142 row_newbcast:1 row_mask:0xf bank_mask:0xf
	v_fmac_f32_dpp v77, v121, v142 row_newbcast:1 row_mask:0xf bank_mask:0xf
	v_fmac_f32_dpp v74, v122, v142 row_newbcast:1 row_mask:0xf bank_mask:0xf
	v_fmac_f32_dpp v75, v123, v142 row_newbcast:1 row_mask:0xf bank_mask:0xf
	v_fmac_f32_dpp v76, v124, v133 row_newbcast:1 row_mask:0xf bank_mask:0xf
	v_fmac_f32_dpp v77, v125, v133 row_newbcast:1 row_mask:0xf bank_mask:0xf
	v_fmac_f32_dpp v74, v126, v133 row_newbcast:1 row_mask:0xf bank_mask:0xf
	v_fmac_f32_dpp v75, v127, v133 row_newbcast:1 row_mask:0xf bank_mask:0xf
	v_fmac_f32_dpp v138, v128, v76 row_newbcast:1 row_mask:0xf bank_mask:0xf
	v_fmac_f32_dpp v139, v129, v77 row_newbcast:1 row_mask:0xf bank_mask:0xf
	v_fmac_f32_dpp v140, v130, v74 row_newbcast:1 row_mask:0xf bank_mask:0xf
	v_fmac_f32_dpp v141, v131, v75 row_newbcast:1 row_mask:0xf bank_mask:0xf
	v_mul_f32_dpp v72, v116, v72 row_newbcast:2 row_mask:0xf bank_mask:0xf
	v_mul_f32_dpp v73, v117, v73 row_newbcast:2 row_mask:0xf bank_mask:0xf
	v_mul_f32_dpp v66, v118, v66 row_newbcast:2 row_mask:0xf bank_mask:0xf
	v_mul_f32_dpp v67, v119, v67 row_newbcast:2 row_mask:0xf bank_mask:0xf
	v_fmac_f32_dpp v72, v120, v142 row_newbcast:2 row_mask:0xf bank_mask:0xf
; template <bool SK>
; __device__ __forceinline__ void scan_task(const float* R, const float* W, const float* KX, const float* KK, const float* KKA, const float* V, float* OUT, float* STT, const float* S0, float* SOUT, int nstep, int lane) {
;     ...
;         float o0 = 0.f, o1 = 0.f;
; #pragma unroll
;         for (int k = 0; k < 64; k += 2) {
;             float x = s[k] * w[k]; x = fmaf(nd, kka[k], x); if (SK) x = fmaf(vt, kx[k], x); s[k] = x; o0 = fmaf(x, r[k], o0);
;             float y = s[k + 1] * w[k + 1]; y = fmaf(nd, kka[k + 1], y); if (SK) y = fmaf(vt, kx[k + 1], y); s[k + 1] = y; o1 = fmaf(y, r[k + 1], o1);
	v_fmac_f32_dpp v73, v121, v142 row_newbcast:2 row_mask:0xf bank_mask:0xf
	v_fmac_f32_dpp v66, v122, v142 row_newbcast:2 row_mask:0xf bank_mask:0xf
	v_fmac_f32_dpp v67, v123, v142 row_newbcast:2 row_mask:0xf bank_mask:0xf
	v_fmac_f32_dpp v72, v124, v133 row_newbcast:2 row_mask:0xf bank_mask:0xf
	v_fmac_f32_dpp v73, v125, v133 row_newbcast:2 row_mask:0xf bank_mask:0xf
	v_fmac_f32_dpp v66, v126, v133 row_newbcast:2 row_mask:0xf bank_mask:0xf
	v_fmac_f32_dpp v67, v127, v133 row_newbcast:2 row_mask:0xf bank_mask:0xf
	v_fmac_f32_dpp v138, v128, v72 row_newbcast:2 row_mask:0xf bank_mask:0xf
	v_fmac_f32_dpp v139, v129, v73 row_newbcast:2 row_mask:0xf bank_mask:0xf
	v_fmac_f32_dpp v140, v130, v66 row_newbcast:2 row_mask:0xf bank_mask:0xf
	v_fmac_f32_dpp v141, v131, v67 row_newbcast:2 row_mask:0xf bank_mask:0xf
	v_mul_f32_dpp v64, v116, v64 row_newbcast:3 row_mask:0xf bank_mask:0xf
	v_mul_f32_dpp v65, v117, v65 row_newbcast:3 row_mask:0xf bank_mask:0xf
	v_mul_f32_dpp v62, v118, v62 row_newbcast:3 row_mask:0xf bank_mask:0xf
	v_mul_f32_dpp v63, v119, v63 row_newbcast:3 row_mask:0xf bank_mask:0xf
	v_fmac_f32_dpp v64, v120, v142 row_newbcast:3 row_mask:0xf bank_mask:0xf
	v_fmac_f32_dpp v65, v121, v142 row_newbcast:3 row_mask:0xf bank_mask:0xf
	v_fmac_f32_dpp v62, v122, v142 row_newbcast:3 row_mask:0xf bank_mask:0xf
	v_fmac_f32_dpp v63, v123, v142 row_newbcast:3 row_mask:0xf bank_mask:0xf
	v_fmac_f32_dpp v64, v124, v133 row_newbcast:3 row_mask:0xf bank_mask:0xf
	v_fmac_f32_dpp v65, v125, v133 row_newbcast:3 row_mask:0xf bank_mask:0xf
	v_fmac_f32_dpp v62, v126, v133 row_newbcast:3 row_mask:0xf bank_mask:0xf
	v_fmac_f32_dpp v63, v127, v133 row_newbcast:3 row_mask:0xf bank_mask:0xf
	v_fmac_f32_dpp v138, v128, v64 row_newbcast:3 row_mask:0xf bank_mask:0xf
	v_fmac_f32_dpp v139, v129, v65 row_newbcast:3 row_mask:0xf bank_mask:0xf
	v_fmac_f32_dpp v140, v130, v62 row_newbcast:3 row_mask:0xf bank_mask:0xf
	v_fmac_f32_dpp v141, v131, v63 row_newbcast:3 row_mask:0xf bank_mask:0xf
	v_mul_f32_dpp v60, v116, v60 row_newbcast:4 row_mask:0xf bank_mask:0xf
	v_mul_f32_dpp v61, v117, v61 row_newbcast:4 row_mask:0xf bank_mask:0xf
	v_mul_f32_dpp v58, v118, v58 row_newbcast:4 row_mask:0xf bank_mask:0xf
	v_mul_f32_dpp v59, v119, v59 row_newbcast:4 row_mask:0xf bank_mask:0xf
	v_fmac_f32_dpp v60, v120, v142 row_newbcast:4 row_mask:0xf bank_mask:0xf
	v_fmac_f32_dpp v61, v121, v142 row_newbcast:4 row_mask:0xf bank_mask:0xf
	v_fmac_f32_dpp v58, v122, v142 row_newbcast:4 row_mask:0xf bank_mask:0xf
	v_fmac_f32_dpp v59, v123, v142 row_newbcast:4 row_mask:0xf bank_mask:0xf
	v_fmac_f32_dpp v60, v124, v133 row_newbcast:4 row_mask:0xf bank_mask:0xf
	v_fmac_f32_dpp v61, v125, v133 row_newbcast:4 row_mask:0xf bank_mask:0xf
	v_fmac_f32_dpp v58, v126, v133 row_newbcast:4 row_mask:0xf bank_mask:0xf
	v_fmac_f32_dpp v59, v127, v133 row_newbcast:4 row_mask:0xf bank_mask:0xf
	v_fmac_f32_dpp v138, v128, v60 row_newbcast:4 row_mask:0xf bank_mask:0xf
	v_fmac_f32_dpp v139, v129, v61 row_newbcast:4 row_mask:0xf bank_mask:0xf
	v_fmac_f32_dpp v140, v130, v58 row_newbcast:4 row_mask:0xf bank_mask:0xf
	v_fmac_f32_dpp v141, v131, v59 row_newbcast:4 row_mask:0xf bank_mask:0xf
	v_mul_f32_dpp v56, v116, v56 row_newbcast:5 row_mask:0xf bank_mask:0xf
	v_mul_f32_dpp v57, v117, v57 row_newbcast:5 row_mask:0xf bank_mask:0xf
	v_mul_f32_dpp v54, v118, v54 row_newbcast:5 row_mask:0xf bank_mask:0xf
	v_mul_f32_dpp v55, v119, v55 row_newbcast:5 row_mask:0xf bank_mask:0xf
	v_fmac_f32_dpp v56, v120, v142 row_newbcast:5 row_mask:0xf bank_mask:0xf
	v_fmac_f32_dpp v57, v121, v142 row_newbcast:5 row_mask:0xf bank_mask:0xf
	v_fmac_f32_dpp v54, v122, v142 row_newbcast:5 row_mask:0xf bank_mask:0xf
	v_fmac_f32_dpp v55, v123, v142 row_newbcast:5 row_mask:0xf bank_mask:0xf
	v_fmac_f32_dpp v56, v124, v133 row_newbcast:5 row_mask:0xf bank_mask:0xf
	v_fmac_f32_dpp v57, v125, v133 row_newbcast:5 row_mask:0xf bank_mask:0xf
	v_fmac_f32_dpp v54, v126, v133 row_newbcast:5 row_mask:0xf bank_mask:0xf
	v_fmac_f32_dpp v55, v127, v133 row_newbcast:5 row_mask:0xf bank_mask:0xf
	v_fmac_f32_dpp v138, v128, v56 row_newbcast:5 row_mask:0xf bank_mask:0xf
	v_fmac_f32_dpp v139, v129, v57 row_newbcast:5 row_mask:0xf bank_mask:0xf
	v_fmac_f32_dpp v140, v130, v54 row_newbcast:5 row_mask:0xf bank_mask:0xf
	v_fmac_f32_dpp v141, v131, v55 row_newbcast:5 row_mask:0xf bank_mask:0xf
	v_mul_f32_dpp v50, v116, v50 row_newbcast:6 row_mask:0xf bank_mask:0xf
	v_mul_f32_dpp v51, v117, v51 row_newbcast:6 row_mask:0xf bank_mask:0xf
	v_mul_f32_dpp v48, v118, v48 row_newbcast:6 row_mask:0xf bank_mask:0xf
	v_mul_f32_dpp v49, v119, v49 row_newbcast:6 row_mask:0xf bank_mask:0xf
	v_fmac_f32_dpp v50, v120, v142 row_newbcast:6 row_mask:0xf bank_mask:0xf
	v_fmac_f32_dpp v51, v121, v142 row_newbcast:6 row_mask:0xf bank_mask:0xf
	v_fmac_f32_dpp v48, v122, v142 row_newbcast:6 row_mask:0xf bank_mask:0xf
	v_fmac_f32_dpp v49, v123, v142 row_newbcast:6 row_mask:0xf bank_mask:0xf
	v_fmac_f32_dpp v50, v124, v133 row_newbcast:6 row_mask:0xf bank_mask:0xf
	v_fmac_f32_dpp v51, v125, v133 row_newbcast:6 row_mask:0xf bank_mask:0xf
	v_fmac_f32_dpp v48, v126, v133 row_newbcast:6 row_mask:0xf bank_mask:0xf
	v_fmac_f32_dpp v49, v127, v133 row_newbcast:6 row_mask:0xf bank_mask:0xf
	v_fmac_f32_dpp v138, v128, v50 row_newbcast:6 row_mask:0xf bank_mask:0xf
	v_fmac_f32_dpp v139, v129, v51 row_newbcast:6 row_mask:0xf bank_mask:0xf
	v_fmac_f32_dpp v140, v130, v48 row_newbcast:6 row_mask:0xf bank_mask:0xf
	v_fmac_f32_dpp v141, v131, v49 row_newbcast:6 row_mask:0xf bank_mask:0xf
	v_mul_f32_dpp v46, v116, v46 row_newbcast:7 row_mask:0xf bank_mask:0xf
	v_mul_f32_dpp v47, v117, v47 row_newbcast:7 row_mask:0xf bank_mask:0xf
; template <bool SK>
; __device__ __forceinline__ void scan_task(const float* R, const float* W, const float* KX, const float* KK, const float* KKA, const float* V, float* OUT, float* STT, const float* S0, float* SOUT, int nstep, int lane) {
;     ...
;         float o0 = 0.f, o1 = 0.f;
; #pragma unroll
;         for (int k = 0; k < 64; k += 2) {
;             float x = s[k] * w[k]; x = fmaf(nd, kka[k], x); if (SK) x = fmaf(vt, kx[k], x); s[k] = x; o0 = fmaf(x, r[k], o0);
;             float y = s[k + 1] * w[k + 1]; y = fmaf(nd, kka[k + 1], y); if (SK) y = fmaf(vt, kx[k + 1], y); s[k + 1] = y; o1 = fmaf(y, r[k + 1], o1);
	v_mul_f32_dpp v44, v118, v44 row_newbcast:7 row_mask:0xf bank_mask:0xf
	v_mul_f32_dpp v45, v119, v45 row_newbcast:7 row_mask:0xf bank_mask:0xf
	v_fmac_f32_dpp v46, v120, v142 row_newbcast:7 row_mask:0xf bank_mask:0xf
	v_fmac_f32_dpp v47, v121, v142 row_newbcast:7 row_mask:0xf bank_mask:0xf
	v_fmac_f32_dpp v44, v122, v142 row_newbcast:7 row_mask:0xf bank_mask:0xf
	v_fmac_f32_dpp v45, v123, v142 row_newbcast:7 row_mask:0xf bank_mask:0xf
	v_fmac_f32_dpp v46, v124, v133 row_newbcast:7 row_mask:0xf bank_mask:0xf
	v_fmac_f32_dpp v47, v125, v133 row_newbcast:7 row_mask:0xf bank_mask:0xf
	v_fmac_f32_dpp v44, v126, v133 row_newbcast:7 row_mask:0xf bank_mask:0xf
	v_fmac_f32_dpp v45, v127, v133 row_newbcast:7 row_mask:0xf bank_mask:0xf
	v_fmac_f32_dpp v138, v128, v46 row_newbcast:7 row_mask:0xf bank_mask:0xf
	v_fmac_f32_dpp v139, v129, v47 row_newbcast:7 row_mask:0xf bank_mask:0xf
	v_fmac_f32_dpp v140, v130, v44 row_newbcast:7 row_mask:0xf bank_mask:0xf
	v_fmac_f32_dpp v141, v131, v45 row_newbcast:7 row_mask:0xf bank_mask:0xf
	v_mul_f32_dpp v42, v116, v42 row_newbcast:8 row_mask:0xf bank_mask:0xf
	v_mul_f32_dpp v43, v117, v43 row_newbcast:8 row_mask:0xf bank_mask:0xf
	v_mul_f32_dpp v40, v118, v40 row_newbcast:8 row_mask:0xf bank_mask:0xf
	v_mul_f32_dpp v41, v119, v41 row_newbcast:8 row_mask:0xf bank_mask:0xf
	v_fmac_f32_dpp v42, v120, v142 row_newbcast:8 row_mask:0xf bank_mask:0xf
	v_fmac_f32_dpp v43, v121, v142 row_newbcast:8 row_mask:0xf bank_mask:0xf
	v_fmac_f32_dpp v40, v122, v142 row_newbcast:8 row_mask:0xf bank_mask:0xf
	v_fmac_f32_dpp v41, v123, v142 row_newbcast:8 row_mask:0xf bank_mask:0xf
	v_fmac_f32_dpp v42, v124, v133 row_newbcast:8 row_mask:0xf bank_mask:0xf
	v_fmac_f32_dpp v43, v125, v133 row_newbcast:8 row_mask:0xf bank_mask:0xf
	v_fmac_f32_dpp v40, v126, v133 row_newbcast:8 row_mask:0xf bank_mask:0xf
	v_fmac_f32_dpp v41, v127, v133 row_newbcast:8 row_mask:0xf bank_mask:0xf
	v_fmac_f32_dpp v138, v128, v42 row_newbcast:8 row_mask:0xf bank_mask:0xf
	v_fmac_f32_dpp v139, v129, v43 row_newbcast:8 row_mask:0xf bank_mask:0xf
	v_fmac_f32_dpp v140, v130, v40 row_newbcast:8 row_mask:0xf bank_mask:0xf
	v_fmac_f32_dpp v141, v131, v41 row_newbcast:8 row_mask:0xf bank_mask:0xf
	v_mul_f32_dpp v38, v116, v38 row_newbcast:9 row_mask:0xf bank_mask:0xf
	v_mul_f32_dpp v39, v117, v39 row_newbcast:9 row_mask:0xf bank_mask:0xf
	v_mul_f32_dpp v36, v118, v36 row_newbcast:9 row_mask:0xf bank_mask:0xf
	v_mul_f32_dpp v37, v119, v37 row_newbcast:9 row_mask:0xf bank_mask:0xf
	v_fmac_f32_dpp v38, v120, v142 row_newbcast:9 row_mask:0xf bank_mask:0xf
	v_fmac_f32_dpp v39, v121, v142 row_newbcast:9 row_mask:0xf bank_mask:0xf
	v_fmac_f32_dpp v36, v122, v142 row_newbcast:9 row_mask:0xf bank_mask:0xf
	v_fmac_f32_dpp v37, v123, v142 row_newbcast:9 row_mask:0xf bank_mask:0xf
	v_fmac_f32_dpp v38, v124, v133 row_newbcast:9 row_mask:0xf bank_mask:0xf
	v_fmac_f32_dpp v39, v125, v133 row_newbcast:9 row_mask:0xf bank_mask:0xf
	v_fmac_f32_dpp v36, v126, v133 row_newbcast:9 row_mask:0xf bank_mask:0xf
	v_fmac_f32_dpp v37, v127, v133 row_newbcast:9 row_mask:0xf bank_mask:0xf
	v_fmac_f32_dpp v138, v128, v38 row_newbcast:9 row_mask:0xf bank_mask:0xf
	v_fmac_f32_dpp v139, v129, v39 row_newbcast:9 row_mask:0xf bank_mask:0xf
	v_fmac_f32_dpp v140, v130, v36 row_newbcast:9 row_mask:0xf bank_mask:0xf
	v_fmac_f32_dpp v141, v131, v37 row_newbcast:9 row_mask:0xf bank_mask:0xf
	v_mul_f32_dpp v32, v116, v32 row_newbcast:10 row_mask:0xf bank_mask:0xf
	v_mul_f32_dpp v33, v117, v33 row_newbcast:10 row_mask:0xf bank_mask:0xf
	v_mul_f32_dpp v30, v118, v30 row_newbcast:10 row_mask:0xf bank_mask:0xf
	v_mul_f32_dpp v31, v119, v31 row_newbcast:10 row_mask:0xf bank_mask:0xf
	v_fmac_f32_dpp v32, v120, v142 row_newbcast:10 row_mask:0xf bank_mask:0xf
	v_fmac_f32_dpp v33, v121, v142 row_newbcast:10 row_mask:0xf bank_mask:0xf
	v_fmac_f32_dpp v30, v122, v142 row_newbcast:10 row_mask:0xf bank_mask:0xf
	v_fmac_f32_dpp v31, v123, v142 row_newbcast:10 row_mask:0xf bank_mask:0xf
	v_fmac_f32_dpp v32, v124, v133 row_newbcast:10 row_mask:0xf bank_mask:0xf
	v_fmac_f32_dpp v33, v125, v133 row_newbcast:10 row_mask:0xf bank_mask:0xf
	v_fmac_f32_dpp v30, v126, v133 row_newbcast:10 row_mask:0xf bank_mask:0xf
	v_fmac_f32_dpp v31, v127, v133 row_newbcast:10 row_mask:0xf bank_mask:0xf
	v_fmac_f32_dpp v138, v128, v32 row_newbcast:10 row_mask:0xf bank_mask:0xf
	v_fmac_f32_dpp v139, v129, v33 row_newbcast:10 row_mask:0xf bank_mask:0xf
	v_fmac_f32_dpp v140, v130, v30 row_newbcast:10 row_mask:0xf bank_mask:0xf
	v_fmac_f32_dpp v141, v131, v31 row_newbcast:10 row_mask:0xf bank_mask:0xf
	v_mul_f32_dpp v28, v116, v28 row_newbcast:11 row_mask:0xf bank_mask:0xf
	v_mul_f32_dpp v29, v117, v29 row_newbcast:11 row_mask:0xf bank_mask:0xf
	v_mul_f32_dpp v26, v118, v26 row_newbcast:11 row_mask:0xf bank_mask:0xf
	v_mul_f32_dpp v27, v119, v27 row_newbcast:11 row_mask:0xf bank_mask:0xf
	v_fmac_f32_dpp v28, v120, v142 row_newbcast:11 row_mask:0xf bank_mask:0xf
	v_fmac_f32_dpp v29, v121, v142 row_newbcast:11 row_mask:0xf bank_mask:0xf
	v_fmac_f32_dpp v26, v122, v142 row_newbcast:11 row_mask:0xf bank_mask:0xf
	v_fmac_f32_dpp v27, v123, v142 row_newbcast:11 row_mask:0xf bank_mask:0xf
	v_fmac_f32_dpp v28, v124, v133 row_newbcast:11 row_mask:0xf bank_mask:0xf
	v_fmac_f32_dpp v29, v125, v133 row_newbcast:11 row_mask:0xf bank_mask:0xf
	v_fmac_f32_dpp v26, v126, v133 row_newbcast:11 row_mask:0xf bank_mask:0xf
	v_fmac_f32_dpp v27, v127, v133 row_newbcast:11 row_mask:0xf bank_mask:0xf
	v_fmac_f32_dpp v138, v128, v28 row_newbcast:11 row_mask:0xf bank_mask:0xf
	v_fmac_f32_dpp v139, v129, v29 row_newbcast:11 row_mask:0xf bank_mask:0xf
; template <bool SK>
; __device__ __forceinline__ void scan_task(const float* R, const float* W, const float* KX, const float* KK, const float* KKA, const float* V, float* OUT, float* STT, const float* S0, float* SOUT, int nstep, int lane) {
;     ...
;         float o0 = 0.f, o1 = 0.f;
; #pragma unroll
;         for (int k = 0; k < 64; k += 2) {
;             float x = s[k] * w[k]; x = fmaf(nd, kka[k], x); if (SK) x = fmaf(vt, kx[k], x); s[k] = x; o0 = fmaf(x, r[k], o0);
;             float y = s[k + 1] * w[k + 1]; y = fmaf(nd, kka[k + 1], y); if (SK) y = fmaf(vt, kx[k + 1], y); s[k + 1] = y; o1 = fmaf(y, r[k + 1], o1);
;         }
;         OUT[(size_t)t * BW + lane] = o0 + o1;
	v_fmac_f32_dpp v140, v130, v26 row_newbcast:11 row_mask:0xf bank_mask:0xf
	v_fmac_f32_dpp v141, v131, v27 row_newbcast:11 row_mask:0xf bank_mask:0xf
	v_mul_f32_dpp v24, v116, v24 row_newbcast:12 row_mask:0xf bank_mask:0xf
	v_mul_f32_dpp v25, v117, v25 row_newbcast:12 row_mask:0xf bank_mask:0xf
	v_mul_f32_dpp v22, v118, v22 row_newbcast:12 row_mask:0xf bank_mask:0xf
	v_mul_f32_dpp v23, v119, v23 row_newbcast:12 row_mask:0xf bank_mask:0xf
	v_fmac_f32_dpp v24, v120, v142 row_newbcast:12 row_mask:0xf bank_mask:0xf
	v_fmac_f32_dpp v25, v121, v142 row_newbcast:12 row_mask:0xf bank_mask:0xf
	v_fmac_f32_dpp v22, v122, v142 row_newbcast:12 row_mask:0xf bank_mask:0xf
	v_fmac_f32_dpp v23, v123, v142 row_newbcast:12 row_mask:0xf bank_mask:0xf
	v_fmac_f32_dpp v24, v124, v133 row_newbcast:12 row_mask:0xf bank_mask:0xf
	v_fmac_f32_dpp v25, v125, v133 row_newbcast:12 row_mask:0xf bank_mask:0xf
	v_fmac_f32_dpp v22, v126, v133 row_newbcast:12 row_mask:0xf bank_mask:0xf
	v_fmac_f32_dpp v23, v127, v133 row_newbcast:12 row_mask:0xf bank_mask:0xf
	v_fmac_f32_dpp v138, v128, v24 row_newbcast:12 row_mask:0xf bank_mask:0xf
	v_fmac_f32_dpp v139, v129, v25 row_newbcast:12 row_mask:0xf bank_mask:0xf
	v_fmac_f32_dpp v140, v130, v22 row_newbcast:12 row_mask:0xf bank_mask:0xf
	v_fmac_f32_dpp v141, v131, v23 row_newbcast:12 row_mask:0xf bank_mask:0xf
	v_mul_f32_dpp v20, v116, v20 row_newbcast:13 row_mask:0xf bank_mask:0xf
	v_mul_f32_dpp v21, v117, v21 row_newbcast:13 row_mask:0xf bank_mask:0xf
	v_mul_f32_dpp v18, v118, v18 row_newbcast:13 row_mask:0xf bank_mask:0xf
	v_mul_f32_dpp v19, v119, v19 row_newbcast:13 row_mask:0xf bank_mask:0xf
	v_fmac_f32_dpp v20, v120, v142 row_newbcast:13 row_mask:0xf bank_mask:0xf
	v_fmac_f32_dpp v21, v121, v142 row_newbcast:13 row_mask:0xf bank_mask:0xf
	v_fmac_f32_dpp v18, v122, v142 row_newbcast:13 row_mask:0xf bank_mask:0xf
	v_fmac_f32_dpp v19, v123, v142 row_newbcast:13 row_mask:0xf bank_mask:0xf
	v_fmac_f32_dpp v20, v124, v133 row_newbcast:13 row_mask:0xf bank_mask:0xf
	v_fmac_f32_dpp v21, v125, v133 row_newbcast:13 row_mask:0xf bank_mask:0xf
	v_fmac_f32_dpp v18, v126, v133 row_newbcast:13 row_mask:0xf bank_mask:0xf
	v_fmac_f32_dpp v19, v127, v133 row_newbcast:13 row_mask:0xf bank_mask:0xf
	v_fmac_f32_dpp v138, v128, v20 row_newbcast:13 row_mask:0xf bank_mask:0xf
	v_fmac_f32_dpp v139, v129, v21 row_newbcast:13 row_mask:0xf bank_mask:0xf
	v_fmac_f32_dpp v140, v130, v18 row_newbcast:13 row_mask:0xf bank_mask:0xf
	v_fmac_f32_dpp v141, v131, v19 row_newbcast:13 row_mask:0xf bank_mask:0xf
	v_mul_f32_dpp v16, v116, v16 row_newbcast:14 row_mask:0xf bank_mask:0xf
	v_mul_f32_dpp v17, v117, v17 row_newbcast:14 row_mask:0xf bank_mask:0xf
	v_mul_f32_dpp v14, v118, v14 row_newbcast:14 row_mask:0xf bank_mask:0xf
	v_mul_f32_dpp v15, v119, v15 row_newbcast:14 row_mask:0xf bank_mask:0xf
	v_fmac_f32_dpp v16, v120, v142 row_newbcast:14 row_mask:0xf bank_mask:0xf
	v_fmac_f32_dpp v17, v121, v142 row_newbcast:14 row_mask:0xf bank_mask:0xf
	v_fmac_f32_dpp v14, v122, v142 row_newbcast:14 row_mask:0xf bank_mask:0xf
	v_fmac_f32_dpp v15, v123, v142 row_newbcast:14 row_mask:0xf bank_mask:0xf
	v_fmac_f32_dpp v16, v124, v133 row_newbcast:14 row_mask:0xf bank_mask:0xf
	v_fmac_f32_dpp v17, v125, v133 row_newbcast:14 row_mask:0xf bank_mask:0xf
	v_fmac_f32_dpp v14, v126, v133 row_newbcast:14 row_mask:0xf bank_mask:0xf
	v_fmac_f32_dpp v15, v127, v133 row_newbcast:14 row_mask:0xf bank_mask:0xf
	v_fmac_f32_dpp v138, v128, v16 row_newbcast:14 row_mask:0xf bank_mask:0xf
	v_fmac_f32_dpp v139, v129, v17 row_newbcast:14 row_mask:0xf bank_mask:0xf
	v_fmac_f32_dpp v140, v130, v14 row_newbcast:14 row_mask:0xf bank_mask:0xf
	v_fmac_f32_dpp v141, v131, v15 row_newbcast:14 row_mask:0xf bank_mask:0xf
	v_mul_f32_dpp v12, v116, v12 row_newbcast:15 row_mask:0xf bank_mask:0xf
	v_mul_f32_dpp v13, v117, v13 row_newbcast:15 row_mask:0xf bank_mask:0xf
	v_mul_f32_dpp v82, v118, v82 row_newbcast:15 row_mask:0xf bank_mask:0xf
	v_mul_f32_dpp v83, v119, v83 row_newbcast:15 row_mask:0xf bank_mask:0xf
	v_fmac_f32_dpp v12, v120, v142 row_newbcast:15 row_mask:0xf bank_mask:0xf
	v_fmac_f32_dpp v13, v121, v142 row_newbcast:15 row_mask:0xf bank_mask:0xf
	v_fmac_f32_dpp v82, v122, v142 row_newbcast:15 row_mask:0xf bank_mask:0xf
	v_fmac_f32_dpp v83, v123, v142 row_newbcast:15 row_mask:0xf bank_mask:0xf
	v_fmac_f32_dpp v12, v124, v133 row_newbcast:15 row_mask:0xf bank_mask:0xf
	v_fmac_f32_dpp v13, v125, v133 row_newbcast:15 row_mask:0xf bank_mask:0xf
	v_fmac_f32_dpp v82, v126, v133 row_newbcast:15 row_mask:0xf bank_mask:0xf
	v_fmac_f32_dpp v83, v127, v133 row_newbcast:15 row_mask:0xf bank_mask:0xf
	v_fmac_f32_dpp v138, v128, v12 row_newbcast:15 row_mask:0xf bank_mask:0xf
	v_fmac_f32_dpp v139, v129, v13 row_newbcast:15 row_mask:0xf bank_mask:0xf
	v_fmac_f32_dpp v140, v130, v82 row_newbcast:15 row_mask:0xf bank_mask:0xf
	v_fmac_f32_dpp v141, v131, v83 row_newbcast:15 row_mask:0xf bank_mask:0xf
	global_load_dwordx4 v[116:119], v143, s[90:91] offset:2048
	global_load_dwordx4 v[120:123], v143, s[94:95] offset:2048
	global_load_dwordx4 v[124:127], v143, s[92:93] offset:2048
	global_load_dwordx4 v[128:131], v143, s[88:89] offset:2048
	global_load_dword v133, v144, s[0:1] offset:2048
	v_add_f32_e32 v138, v138, v140
	v_add_f32_e32 v139, v139, v141
	v_add_f32_e32 v138, v138, v139
	global_store_dword v144, v138, s[2:3] offset:2048
	s_add_u32 s96, s96, 0x1000
	s_addc_u32 s97, s97, 0
	s_add_u32 s90, s90, 0x1000
	s_addc_u32 s91, s91, 0
	s_add_u32 s94, s94, 0x1000
	s_addc_u32 s95, s95, 0
	s_add_u32 s92, s92, 0x1000
	s_addc_u32 s93, s93, 0
	s_add_u32 s88, s88, 0x1000
	s_addc_u32 s89, s89, 0
	s_add_u32 s0, s0, 0x1000
	s_addc_u32 s1, s1, 0
	s_add_u32 s2, s2, 0x1000
	s_addc_u32 s3, s3, 0
	s_add_i32 s20, s20, 1
	s_cmp_lg_u32 s20, 32
	s_cbranch_scc1 .Lscan_s_loop
; template <bool SK>
; __device__ __forceinline__ void scan_task(const float* R, const float* W, const float* KX, const float* KK, const float* KKA, const float* V, float* OUT, float* STT, const float* S0, float* SOUT, int nstep, int lane) {
;     ...
;     asm volatile("" :: "v"(pf0), "v"(pf1), "v"(pf2), "v"(pf3), "v"(pf4));
;     if (STT) {
; #pragma unroll
;         for (int k = 0; k < 64; ++k) STT[k * 64 + lane] = s[k];
	s_waitcnt vmcnt(0)
	v_mov_b32_e32 v1, v145
	s_nop 0
	ds_read_b32 v92, v1 offset:0
	ds_read_b32 v93, v1 offset:256
	ds_read_b32 v94, v1 offset:512
	ds_read_b32 v95, v1 offset:768
	ds_read_b32 v96, v1 offset:1024
	ds_read_b32 v97, v1 offset:1280
	ds_read_b32 v98, v1 offset:1536
	ds_read_b32 v99, v1 offset:1792
	ds_read_b32 v100, v1 offset:2048
	ds_read_b32 v101, v1 offset:2304
	ds_read_b32 v102, v1 offset:2560
	ds_read_b32 v103, v1 offset:2816
	ds_read_b32 v104, v1 offset:3072
	ds_read_b32 v105, v1 offset:3328
	ds_read_b32 v106, v1 offset:3584
	ds_read_b32 v107, v1 offset:3840
	ds_read_b32 v108, v1 offset:4096
	ds_read_b32 v109, v1 offset:4352
	ds_read_b32 v110, v1 offset:4608
	ds_read_b32 v111, v1 offset:4864
	ds_read_b32 v112, v1 offset:5120
	ds_read_b32 v113, v1 offset:5376
	ds_read_b32 v114, v1 offset:5632
	ds_read_b32 v115, v1 offset:5888
	ds_read_b32 v116, v1 offset:6144
	ds_read_b32 v117, v1 offset:6400
	ds_read_b32 v118, v1 offset:6656
	ds_read_b32 v119, v1 offset:6912
	ds_read_b32 v120, v1 offset:7168
	ds_read_b32 v121, v1 offset:7424
	ds_read_b32 v122, v1 offset:7680
	ds_read_b32 v123, v1 offset:7936
	ds_read_b32 v124, v1 offset:8192
	ds_read_b32 v125, v1 offset:8448
	ds_read_b32 v126, v1 offset:8704
	ds_read_b32 v127, v1 offset:8960
	ds_read_b32 v128, v1 offset:9216
	ds_read_b32 v129, v1 offset:9472
	ds_read_b32 v130, v1 offset:9728
	ds_read_b32 v131, v1 offset:9984
	ds_read_b32 v132, v1 offset:10240
	ds_read_b32 v133, v1 offset:10496
	ds_read_b32 v134, v1 offset:10752
	ds_read_b32 v135, v1 offset:11008
	ds_read_b32 v136, v1 offset:11264
	ds_read_b32 v137, v1 offset:11520
	ds_read_b32 v138, v1 offset:11776
	ds_read_b32 v139, v1 offset:12032
	ds_read_b32 v140, v1 offset:12288
	ds_read_b32 v141, v1 offset:12544
	ds_read_b32 v142, v1 offset:12800
	ds_read_b32 v143, v1 offset:13056
	ds_read_b32 v144, v1 offset:13312
	ds_read_b32 v145, v1 offset:13568
	s_waitcnt lgkmcnt(0)
	v_readlane_b32 s8, v255, 23
	v_lshlrev_b64 v[52:53], 2, v[70:71]
	v_readlane_b32 s9, v255, 24
	s_mov_b64 s[0:1], 0x44b00000
	v_readlane_b32 s82, v254, 57
	v_lshl_add_u64 v[52:53], s[8:9], 0, v[52:53]
	v_lshl_add_u64 v[52:53], v[68:69], 2, v[52:53]
	v_add_co_u32_e32 v86, vcc, 0x44b00000, v52
	v_lshl_add_u64 v[84:85], v[52:53], 0, s[0:1]
	s_nop 0
	v_addc_co_u32_e32 v87, vcc, 0, v53, vcc
	s_mov_b32 s0, 0x44b01000
	global_store_dword v[86:87], v80, off
	global_store_dword v[84:85], v81, off offset:256
	global_store_dword v[84:85], v78, off offset:512
	global_store_dword v[84:85], v79, off offset:768
	global_store_dword v[84:85], v76, off offset:1024
	global_store_dword v[84:85], v77, off offset:1280
	global_store_dword v[84:85], v74, off offset:1536
	global_store_dword v[84:85], v75, off offset:1792
	global_store_dword v[84:85], v72, off offset:2048
	global_store_dword v[84:85], v73, off offset:2304
	global_store_dword v[84:85], v66, off offset:2560
	global_store_dword v[84:85], v67, off offset:2816
	global_store_dword v[84:85], v64, off offset:3072
	global_store_dword v[84:85], v65, off offset:3328
	global_store_dword v[84:85], v62, off offset:3584
	global_store_dword v[84:85], v63, off offset:3840
	v_add_co_u32_e32 v62, vcc, s0, v52
	s_mov_b32 s0, 0x44b02000
	s_nop 0
	v_addc_co_u32_e32 v63, vcc, 0, v53, vcc
	v_add_co_u32_e32 v64, vcc, s0, v52
	s_mov_b32 s0, 0x44b03000
	s_nop 0
	v_addc_co_u32_e32 v65, vcc, 0, v53, vcc
	global_store_dword v[64:65], v60, off offset:-4096
	global_store_dword v[62:63], v61, off offset:256
	global_store_dword v[62:63], v58, off offset:512
	global_store_dword v[62:63], v59, off offset:768
	global_store_dword v[62:63], v56, off offset:1024
	global_store_dword v[62:63], v57, off offset:1280
	global_store_dword v[62:63], v54, off offset:1536
	global_store_dword v[62:63], v55, off offset:1792
	global_store_dword v[62:63], v50, off offset:2048
	global_store_dword v[62:63], v51, off offset:2304
	global_store_dword v[62:63], v48, off offset:2560
	global_store_dword v[62:63], v49, off offset:2816
	global_store_dword v[62:63], v46, off offset:3072
	global_store_dword v[62:63], v47, off offset:3328
	global_store_dword v[62:63], v44, off offset:3584
	global_store_dword v[62:63], v45, off offset:3840
	global_store_dword v[64:65], v42, off
	global_store_dword v[64:65], v43, off offset:256
	global_store_dword v[64:65], v40, off offset:512
	global_store_dword v[64:65], v41, off offset:768
	global_store_dword v[64:65], v38, off offset:1024
	global_store_dword v[64:65], v39, off offset:1280
	global_store_dword v[64:65], v36, off offset:1536
	global_store_dword v[64:65], v37, off offset:1792
	global_store_dword v[64:65], v32, off offset:2048
	global_store_dword v[64:65], v33, off offset:2304
	global_store_dword v[64:65], v30, off offset:2560
	global_store_dword v[64:65], v31, off offset:2816
	global_store_dword v[64:65], v28, off offset:3072
	global_store_dword v[64:65], v29, off offset:3328
	global_store_dword v[64:65], v26, off offset:3584
	global_store_dword v[64:65], v27, off offset:3840
	v_add_co_u32_e32 v26, vcc, s0, v52
	v_readlane_b32 s84, v254, 59
	v_readlane_b32 s86, v254, 61
	v_readlane_b32 s88, v254, 63
	v_readlane_b32 s76, v255, 1
	v_readlane_b32 s78, v255, 3
	v_readlane_b32 s90, v255, 5
	v_readlane_b32 s56, v255, 7
	v_readlane_b32 s60, v255, 9
	v_readlane_b32 s74, v255, 15
	s_movk_i32 s64, 0xf800
	v_addc_co_u32_e32 v27, vcc, 0, v53, vcc
	s_mov_b64 s[0:1], 0
	v_readlane_b32 s93, v254, 40
	v_readlane_b32 s96, v254, 41
	v_readlane_b32 s97, v254, 42
	v_readlane_b32 s94, v251, 3
	v_readlane_b32 s80, v254, 43
	v_readlane_b32 s81, v254, 44
	v_readlane_b32 s83, v254, 58
	v_readlane_b32 s85, v254, 60
	v_readlane_b32 s87, v254, 62
	v_readlane_b32 s89, v255, 0
	v_readlane_b32 s77, v255, 2
	v_readlane_b32 s79, v255, 4
	v_readlane_b32 s91, v255, 6
	v_readlane_b32 s57, v255, 8
	v_readlane_b32 s61, v255, 10
	v_readlane_b32 s62, v255, 11
	v_readlane_b32 s63, v255, 12
	v_readlane_b32 s92, v255, 13
	s_movk_i32 s95, 0x4000
	s_mov_b32 s67, 0xf800000
	s_movk_i32 s68, 0x2a00
	s_movk_i32 s69, 0x1000
	s_movk_i32 s70, 0x1c00
	s_mov_b32 s71, 0x92492493
	v_readlane_b32 s72, v255, 14
	v_readlane_b32 s75, v255, 16
	s_mov_b32 s65, -1
	v_readlane_b32 s66, v255, 22
	v_readlane_b32 s7, v255, 27
	global_store_dword v[26:27], v24, off
	global_store_dword v[26:27], v25, off offset:256
	global_store_dword v[26:27], v22, off offset:512
	global_store_dword v[26:27], v23, off offset:768
	global_store_dword v[26:27], v20, off offset:1024
	global_store_dword v[26:27], v21, off offset:1280
	global_store_dword v[26:27], v18, off offset:1536
	global_store_dword v[26:27], v19, off offset:1792
	global_store_dword v[26:27], v16, off offset:2048
	global_store_dword v[26:27], v17, off offset:2304
	global_store_dword v[26:27], v14, off offset:2560
	global_store_dword v[26:27], v15, off offset:2816
	global_store_dword v[26:27], v12, off offset:3072
	global_store_dword v[26:27], v13, off offset:3328
	global_store_dword v[26:27], v82, off offset:3584
	global_store_dword v[26:27], v83, off offset:3840
; __device__ __forceinline__ const float* uni_ptr(const float* p) { const unsigned long long v = (unsigned long long)p; const unsigned lo = __builtin_amdgcn_readfirstlane((unsigned)v), hi = __builtin_amdgcn_readfirstlane((unsigned)(v >> 32)); return (const float*)(((unsigned long long)hi << 32) | lo); }
; template <bool SK>
; __device__ __forceinline__ void scan_task(const float* R, const float* W, const float* KX, const float* KK, const float* KKA, const float* V, float* OUT, float* STT, const float* S0, float* SOUT, int nstep, int lane) {
;     ...
;         for (int k = 0; k < 64; ++k) s[k] = SK ? 0.f : (k == lane ? 1.f : 0.f);
; __device__ __forceinline__ void scan_item(Frame& F, int l, int item, unsigned char* ws) {
;     ...
;     else scan_task<false>(uni_ptr(R), uni_ptr(W), uni_ptr(KX), uni_ptr(KK), uni_ptr(KKA), V, (float*)(ws + WS_PR) + ro, nullptr, nullptr, (float*)(ws + WS_PC) + so, 64, F.lane);
.LBB0_909:
	s_and_b64 vcc, exec, s[0:1]
	s_cbranch_vccz .LBB0_903
	v_cmp_eq_u32_e32 vcc, 1, v68
	v_readfirstlane_b32 s37, v3
	v_readfirstlane_b32 s36, v2
	v_cndmask_b32_e64 v3, 0, 1.0, vcc
	v_cmp_eq_u32_e32 vcc, 0, v68
	v_readfirstlane_b32 s35, v5
	v_readfirstlane_b32 s34, v4
	v_cndmask_b32_e64 v2, 0, 1.0, vcc
	v_cmp_eq_u32_e32 vcc, 3, v68
	v_readfirstlane_b32 s27, v7
	v_readfirstlane_b32 s26, v6
	v_cndmask_b32_e64 v5, 0, 1.0, vcc
	v_cmp_eq_u32_e32 vcc, 2, v68
	v_readfirstlane_b32 s3, v9
	v_readfirstlane_b32 s2, v8
	v_cndmask_b32_e64 v4, 0, 1.0, vcc
	v_cmp_eq_u32_e32 vcc, 5, v68
	v_readfirstlane_b32 s1, v11
	v_readfirstlane_b32 s0, v10
	v_cndmask_b32_e64 v7, 0, 1.0, vcc
	v_cmp_eq_u32_e32 vcc, 4, v68
	s_add_i32 s4, s33, s28
	s_lshl_b32 s6, s25, 6
	v_cndmask_b32_e64 v6, 0, 1.0, vcc
	v_cmp_eq_u32_e32 vcc, 7, v68
	s_ashr_i32 s5, s4, 31
	s_add_i32 s25, s7, s6
	v_cndmask_b32_e64 v9, 0, 1.0, vcc
	v_cmp_eq_u32_e32 vcc, 6, v68
	s_lshl_b64 s[4:5], s[4:5], 11
	s_lshl_b32 s6, s25, 2
	v_cndmask_b32_e64 v8, 0, 1.0, vcc
	v_cmp_eq_u32_e32 vcc, 9, v68
	s_add_u32 s6, s8, s6
	s_addc_u32 s7, s9, 0
	v_cndmask_b32_e64 v11, 0, 1.0, vcc
	v_cmp_eq_u32_e32 vcc, 8, v68
	s_add_u32 s4, s6, s4
	s_addc_u32 s5, s7, s5
	v_cndmask_b32_e64 v10, 0, 1.0, vcc
	v_cmp_eq_u32_e32 vcc, 11, v68
	v_lshl_add_u64 v[72:73], v[68:69], 2, s[4:5]
	s_mov_b64 s[4:5], 0x42900000
	v_cndmask_b32_e64 v13, 0, 1.0, vcc
	v_cmp_eq_u32_e32 vcc, 10, v68
	s_mov_b32 s31, 0
	s_mov_b64 s[82:83], s[8:9]
	v_cndmask_b32_e64 v12, 0, 1.0, vcc
	v_cmp_eq_u32_e32 vcc, 13, v68
	v_lshl_add_u64 v[72:73], v[72:73], 0, s[4:5]
	v_mov_b32_e32 v1, 0
	v_cndmask_b32_e64 v15, 0, 1.0, vcc
	v_cmp_eq_u32_e32 vcc, 12, v68
	s_mov_b64 s[72:73], s[34:35]
	s_mov_b64 s[74:75], s[2:3]
	v_cndmask_b32_e64 v14, 0, 1.0, vcc
	v_cmp_eq_u32_e32 vcc, 15, v68
	s_mov_b64 s[76:77], s[36:37]
	s_mov_b64 s[78:79], s[0:1]
	v_cndmask_b32_e64 v17, 0, 1.0, vcc
	v_cmp_eq_u32_e32 vcc, 14, v68
	v_mov_b32_e32 v34, 0
	v_mov_b32_e32 v78, 0
	v_cndmask_b32_e64 v16, 0, 1.0, vcc
	v_cmp_eq_u32_e32 vcc, 17, v68
	v_mov_b32_e32 v79, 0
	v_mov_b32_e32 v80, 0
	v_cndmask_b32_e64 v19, 0, 1.0, vcc
	v_cmp_eq_u32_e32 vcc, 16, v68
	s_mov_b32 s25, 0
	s_mov_b64 s[38:39], 0x800
	v_cndmask_b32_e64 v18, 0, 1.0, vcc
	v_cmp_eq_u32_e32 vcc, 19, v68
	s_nop 1
	v_cndmask_b32_e64 v21, 0, 1.0, vcc
	v_cmp_eq_u32_e32 vcc, 18, v68
	s_nop 1
	v_cndmask_b32_e64 v20, 0, 1.0, vcc
	v_cmp_eq_u32_e32 vcc, 21, v68
	s_nop 1
	v_cndmask_b32_e64 v23, 0, 1.0, vcc
	v_cmp_eq_u32_e32 vcc, 20, v68
	s_nop 1
	v_cndmask_b32_e64 v22, 0, 1.0, vcc
	v_cmp_eq_u32_e32 vcc, 23, v68
	s_nop 1
	v_cndmask_b32_e64 v25, 0, 1.0, vcc
	v_cmp_eq_u32_e32 vcc, 22, v68
	s_nop 1
	v_cndmask_b32_e64 v24, 0, 1.0, vcc
	v_cmp_eq_u32_e32 vcc, 25, v68
	s_nop 1
	v_cndmask_b32_e64 v27, 0, 1.0, vcc
	v_cmp_eq_u32_e32 vcc, 24, v68
	s_nop 1
	v_cndmask_b32_e64 v26, 0, 1.0, vcc
	v_cmp_eq_u32_e32 vcc, 27, v68
	s_nop 1
	v_cndmask_b32_e64 v29, 0, 1.0, vcc
	v_cmp_eq_u32_e32 vcc, 26, v68
	s_nop 1
	v_cndmask_b32_e64 v28, 0, 1.0, vcc
	v_cmp_eq_u32_e32 vcc, 29, v68
	s_nop 1
	v_cndmask_b32_e64 v31, 0, 1.0, vcc
	v_cmp_eq_u32_e32 vcc, 28, v68
	s_nop 1
	v_cndmask_b32_e64 v30, 0, 1.0, vcc
	v_cmp_eq_u32_e32 vcc, 31, v68
	s_nop 1
	v_cndmask_b32_e64 v33, 0, 1.0, vcc
	v_cmp_eq_u32_e32 vcc, 30, v68
	s_nop 1
	v_cndmask_b32_e64 v32, 0, 1.0, vcc
	v_cmp_eq_u32_e32 vcc, 33, v68
	s_waitcnt vmcnt(0)
	s_nop 0
	v_cndmask_b32_e64 v37, 0, 1.0, vcc
	v_cmp_eq_u32_e32 vcc, 32, v68
	s_nop 1
	v_cndmask_b32_e64 v36, 0, 1.0, vcc
	v_cmp_eq_u32_e32 vcc, 35, v68
	s_nop 1
	v_cndmask_b32_e64 v39, 0, 1.0, vcc
	v_cmp_eq_u32_e32 vcc, 34, v68
	s_nop 1
	v_cndmask_b32_e64 v38, 0, 1.0, vcc
	v_cmp_eq_u32_e32 vcc, 37, v68
	s_nop 1
	v_cndmask_b32_e64 v41, 0, 1.0, vcc
	v_cmp_eq_u32_e32 vcc, 36, v68
	s_nop 1
	v_cndmask_b32_e64 v40, 0, 1.0, vcc
	v_cmp_eq_u32_e32 vcc, 39, v68
	s_nop 1
	v_cndmask_b32_e64 v43, 0, 1.0, vcc
	v_cmp_eq_u32_e32 vcc, 38, v68
	s_nop 1
	v_cndmask_b32_e64 v42, 0, 1.0, vcc
	v_cmp_eq_u32_e32 vcc, 41, v68
	s_nop 1
	v_cndmask_b32_e64 v45, 0, 1.0, vcc
	v_cmp_eq_u32_e32 vcc, 40, v68
	s_nop 1
	v_cndmask_b32_e64 v44, 0, 1.0, vcc
	v_cmp_eq_u32_e32 vcc, 43, v68
	s_nop 1
	v_cndmask_b32_e64 v47, 0, 1.0, vcc
	v_cmp_eq_u32_e32 vcc, 42, v68
	s_nop 1
	v_cndmask_b32_e64 v46, 0, 1.0, vcc
	v_cmp_eq_u32_e32 vcc, 45, v68
	s_nop 1
	v_cndmask_b32_e64 v49, 0, 1.0, vcc
	v_cmp_eq_u32_e32 vcc, 44, v68
	s_nop 1
	v_cndmask_b32_e64 v48, 0, 1.0, vcc
	v_cmp_eq_u32_e32 vcc, 47, v68
	s_nop 1
	v_cndmask_b32_e64 v51, 0, 1.0, vcc
	v_cmp_eq_u32_e32 vcc, 46, v68
	s_nop 1
	v_cndmask_b32_e64 v50, 0, 1.0, vcc
	v_cmp_eq_u32_e32 vcc, 49, v68
	s_nop 1
	v_cndmask_b32_e64 v53, 0, 1.0, vcc
	v_cmp_eq_u32_e32 vcc, 48, v68
	s_nop 1
	v_cndmask_b32_e64 v52, 0, 1.0, vcc
	v_cmp_eq_u32_e32 vcc, 51, v68
	s_nop 1
	v_cndmask_b32_e64 v55, 0, 1.0, vcc
	v_cmp_eq_u32_e32 vcc, 50, v68
	s_nop 1
	v_cndmask_b32_e64 v54, 0, 1.0, vcc
	v_cmp_eq_u32_e32 vcc, 53, v68
	s_nop 1
	v_cndmask_b32_e64 v57, 0, 1.0, vcc
	v_cmp_eq_u32_e32 vcc, 52, v68
	s_nop 1
	v_cndmask_b32_e64 v56, 0, 1.0, vcc
	v_cmp_eq_u32_e32 vcc, 55, v68
	s_nop 1
	v_cndmask_b32_e64 v59, 0, 1.0, vcc
	v_cmp_eq_u32_e32 vcc, 54, v68
	s_nop 1
	v_cndmask_b32_e64 v58, 0, 1.0, vcc
	v_cmp_eq_u32_e32 vcc, 57, v68
	s_nop 1
	v_cndmask_b32_e64 v61, 0, 1.0, vcc
	v_cmp_eq_u32_e32 vcc, 56, v68
	s_nop 1
	v_cndmask_b32_e64 v60, 0, 1.0, vcc
	v_cmp_eq_u32_e32 vcc, 59, v68
	s_nop 1
	v_cndmask_b32_e64 v63, 0, 1.0, vcc
	v_cmp_eq_u32_e32 vcc, 58, v68
	s_nop 1
	v_cndmask_b32_e64 v62, 0, 1.0, vcc
	v_cmp_eq_u32_e32 vcc, 61, v68
	s_nop 1
	v_cndmask_b32_e64 v65, 0, 1.0, vcc
	v_cmp_eq_u32_e32 vcc, 60, v68
	s_nop 1
	v_cndmask_b32_e64 v64, 0, 1.0, vcc
	v_cmp_eq_u32_e32 vcc, 63, v68
	s_nop 1
	v_cndmask_b32_e64 v67, 0, 1.0, vcc
; template <bool SK>
; __device__ __forceinline__ void scan_task(const float* R, const float* W, const float* KX, const float* KK, const float* KKA, const float* V, float* OUT, float* STT, const float* S0, float* SOUT, int nstep, int lane) {
;     ...
;         for (int k = 0; k < 64; ++k) s[k] = SK ? 0.f : (k == lane ? 1.f : 0.f);
;     }
;     float pf0 = 0.f, pf1 = 0.f, pf2 = 0.f, pf3 = 0.f, pf4 = 0.f;
;     for (int t = 0; t < nstep; ++t) {
;         asm volatile("" :: "v"(pf0), "v"(pf1), "v"(pf2), "v"(pf3), "v"(pf4));
;         { const int tp = (t + 2 < nstep) ? t + 2 : t; const size_t po = (size_t)tp * BW + lane;
;           pf0 = KK[po]; pf1 = W[po]; pf2 = KKA[po]; pf3 = KX[po]; pf4 = R[po]; }
;         cfloat* kk = (cfloat*)(KK + (size_t)t * BW); cfloat* w = (cfloat*)(W + (size_t)t * BW); cfloat* kka = (cfloat*)(KKA + (size_t)t * BW);
;         cfloat* kx = (cfloat*)(KX + (size_t)t * BW); cfloat* r = (cfloat*)(R + (size_t)t * BW);
;         float d0 = 0.f, d1 = 0.f;
; #pragma unroll
;         for (int k = 0; k < 64; k += 2) { d0 = fmaf(s[k], kk[k], d0); d1 = fmaf(s[k + 1], kk[k + 1], d1); }
	v_cmp_eq_u32_e32 vcc, 62, v68
	s_nop 1
	v_cndmask_b32_e64 v66, 0, 1.0, vcc
	v_readlane_b32 s25, v251, 3
	s_nop 3
	s_mul_i32 s25, s25, 0x3800
	s_nop 0
	v_lshl_add_u32 v1, v68, 2, s25
	ds_write_b32 v1, v92 offset:0
	ds_write_b32 v1, v93 offset:256
	ds_write_b32 v1, v94 offset:512
	ds_write_b32 v1, v95 offset:768
	ds_write_b32 v1, v96 offset:1024
	ds_write_b32 v1, v97 offset:1280
	ds_write_b32 v1, v98 offset:1536
	ds_write_b32 v1, v99 offset:1792
	ds_write_b32 v1, v100 offset:2048
	ds_write_b32 v1, v101 offset:2304
	ds_write_b32 v1, v102 offset:2560
	ds_write_b32 v1, v103 offset:2816
	ds_write_b32 v1, v104 offset:3072
	ds_write_b32 v1, v105 offset:3328
	ds_write_b32 v1, v106 offset:3584
	ds_write_b32 v1, v107 offset:3840
	ds_write_b32 v1, v108 offset:4096
	ds_write_b32 v1, v109 offset:4352
	ds_write_b32 v1, v110 offset:4608
	ds_write_b32 v1, v111 offset:4864
	ds_write_b32 v1, v112 offset:5120
	ds_write_b32 v1, v113 offset:5376
	ds_write_b32 v1, v114 offset:5632
	ds_write_b32 v1, v115 offset:5888
	ds_write_b32 v1, v116 offset:6144
	ds_write_b32 v1, v117 offset:6400
	ds_write_b32 v1, v118 offset:6656
	ds_write_b32 v1, v119 offset:6912
	ds_write_b32 v1, v120 offset:7168
	ds_write_b32 v1, v121 offset:7424
	ds_write_b32 v1, v122 offset:7680
	ds_write_b32 v1, v123 offset:7936
	ds_write_b32 v1, v124 offset:8192
	ds_write_b32 v1, v125 offset:8448
	ds_write_b32 v1, v126 offset:8704
	ds_write_b32 v1, v127 offset:8960
	ds_write_b32 v1, v128 offset:9216
	ds_write_b32 v1, v129 offset:9472
	ds_write_b32 v1, v130 offset:9728
	ds_write_b32 v1, v131 offset:9984
	ds_write_b32 v1, v132 offset:10240
	ds_write_b32 v1, v133 offset:10496
	ds_write_b32 v1, v134 offset:10752
	ds_write_b32 v1, v135 offset:11008
	v_readfirstlane_b32 s0, v72
	v_readfirstlane_b32 s1, v73
	s_waitcnt lgkmcnt(0)
	v_mov_b32_e32 v135, v1
	v_and_b32_e32 v133, 15, v68
	v_lshlrev_b32_e32 v133, 4, v133
	v_lshlrev_b32_e32 v134, 2, v68
	s_nop 0
	s_mov_b64 s[2:3], s[72:73]
	s_load_dwordx16 s[4:19], s[2:3], 0x0
	s_load_dwordx16 s[40:55], s[2:3], 0x40
	s_load_dwordx16 s[56:71], s[2:3], 0x80
	global_load_dwordx4 v[92:95], v133, s[72:73]
	global_load_dwordx4 v[96:99], v133, s[74:75]
	global_load_dwordx4 v[100:103], v133, s[76:77]
	global_load_dwordx4 v[104:107], v133, s[78:79]
	global_load_dwordx4 v[108:111], v133, s[72:73] offset:2048
	global_load_dwordx4 v[112:115], v133, s[74:75] offset:2048
	global_load_dwordx4 v[116:119], v133, s[76:77] offset:2048
	global_load_dwordx4 v[120:123], v133, s[78:79] offset:2048
	s_add_u32 s72, s72, 0x1000
	s_addc_u32 s73, s73, 0
	s_add_u32 s74, s74, 0x1000
	s_addc_u32 s75, s75, 0
	s_add_u32 s76, s76, 0x1000
	s_addc_u32 s77, s77, 0
	s_add_u32 s78, s78, 0x1000
	s_addc_u32 s79, s79, 0
	s_mov_b32 s20, 0
	s_waitcnt vmcnt(0)
.Lscan_p_loop:
	s_waitcnt vmcnt(6) lgkmcnt(0)
	v_pk_mul_f32 v[124:125], v[2:3], s[4:5]
	v_pk_mul_f32 v[126:127], v[4:5], s[6:7]
	v_pk_fma_f32 v[124:125], v[6:7], s[8:9], v[124:125]
	v_pk_fma_f32 v[126:127], v[8:9], s[10:11], v[126:127]
	v_pk_fma_f32 v[124:125], v[10:11], s[12:13], v[124:125]
	v_pk_fma_f32 v[126:127], v[12:13], s[14:15], v[126:127]
	v_pk_fma_f32 v[124:125], v[14:15], s[16:17], v[124:125]
	v_pk_fma_f32 v[126:127], v[16:17], s[18:19], v[126:127]
	v_pk_fma_f32 v[124:125], v[18:19], s[40:41], v[124:125]
	v_pk_fma_f32 v[126:127], v[20:21], s[42:43], v[126:127]
	v_pk_fma_f32 v[124:125], v[22:23], s[44:45], v[124:125]
	v_pk_fma_f32 v[126:127], v[24:25], s[46:47], v[126:127]
	v_pk_fma_f32 v[124:125], v[26:27], s[48:49], v[124:125]
	v_pk_fma_f32 v[126:127], v[28:29], s[50:51], v[126:127]
	v_pk_fma_f32 v[124:125], v[30:31], s[52:53], v[124:125]
	v_pk_fma_f32 v[126:127], v[32:33], s[54:55], v[126:127]
	v_pk_fma_f32 v[124:125], v[36:37], s[56:57], v[124:125]
	v_pk_fma_f32 v[126:127], v[38:39], s[58:59], v[126:127]
	v_pk_fma_f32 v[124:125], v[40:41], s[60:61], v[124:125]
	v_pk_fma_f32 v[126:127], v[42:43], s[62:63], v[126:127]
	v_pk_fma_f32 v[124:125], v[44:45], s[64:65], v[124:125]
	v_pk_fma_f32 v[126:127], v[46:47], s[66:67], v[126:127]
	v_pk_fma_f32 v[124:125], v[48:49], s[68:69], v[124:125]
	v_pk_fma_f32 v[126:127], v[50:51], s[70:71], v[126:127]
	s_nop 0
	v_fmac_f32_dpp v124, v92, v52 row_newbcast:12 row_mask:0xf bank_mask:0xf
	v_fmac_f32_dpp v125, v93, v53 row_newbcast:12 row_mask:0xf bank_mask:0xf
	v_fmac_f32_dpp v126, v94, v54 row_newbcast:12 row_mask:0xf bank_mask:0xf
	v_fmac_f32_dpp v127, v95, v55 row_newbcast:12 row_mask:0xf bank_mask:0xf
	v_fmac_f32_dpp v124, v92, v56 row_newbcast:13 row_mask:0xf bank_mask:0xf
	v_fmac_f32_dpp v125, v93, v57 row_newbcast:13 row_mask:0xf bank_mask:0xf
	v_fmac_f32_dpp v126, v94, v58 row_newbcast:13 row_mask:0xf bank_mask:0xf
	v_fmac_f32_dpp v127, v95, v59 row_newbcast:13 row_mask:0xf bank_mask:0xf
	v_fmac_f32_dpp v124, v92, v60 row_newbcast:14 row_mask:0xf bank_mask:0xf
	v_fmac_f32_dpp v125, v93, v61 row_newbcast:14 row_mask:0xf bank_mask:0xf
	v_fmac_f32_dpp v126, v94, v62 row_newbcast:14 row_mask:0xf bank_mask:0xf
	v_fmac_f32_dpp v127, v95, v63 row_newbcast:14 row_mask:0xf bank_mask:0xf
	v_fmac_f32_dpp v124, v92, v64 row_newbcast:15 row_mask:0xf bank_mask:0xf
	v_fmac_f32_dpp v125, v93, v65 row_newbcast:15 row_mask:0xf bank_mask:0xf
	v_fmac_f32_dpp v126, v94, v66 row_newbcast:15 row_mask:0xf bank_mask:0xf
	v_fmac_f32_dpp v127, v95, v67 row_newbcast:15 row_mask:0xf bank_mask:0xf
	global_load_dwordx4 v[92:95], v133, s[72:73]
	s_add_u32 s2, s2, 0x800
	s_addc_u32 s3, s3, 0
	s_nop 1
	s_load_dwordx16 s[4:19], s[2:3], 0x0
	s_load_dwordx16 s[40:55], s[2:3], 0x40
	s_load_dwordx16 s[56:71], s[2:3], 0x80
	v_add_f32_e32 v124, v124, v126
	v_add_f32_e32 v125, v125, v127
	v_add_f32_e32 v132, v124, v125
; template <bool SK>
; __device__ __forceinline__ void scan_task(const float* R, const float* W, const float* KX, const float* KK, const float* KKA, const float* V, float* OUT, float* STT, const float* S0, float* SOUT, int nstep, int lane) {
;     ...
;         const float nd = -(d0 + d1);
;         const float vt = SK ? V[(size_t)t * BW + lane] : 0.f;
;         float o0 = 0.f, o1 = 0.f;
; #pragma unroll
;         for (int k = 0; k < 64; k += 2) {
;             float x = s[k] * w[k]; x = fmaf(nd, kka[k], x); if (SK) x = fmaf(vt, kx[k], x); s[k] = x; o0 = fmaf(x, r[k], o0);
;             float y = s[k + 1] * w[k + 1]; y = fmaf(nd, kka[k + 1], y); if (SK) y = fmaf(vt, kx[k + 1], y); s[k + 1] = y; o1 = fmaf(y, r[k + 1], o1);
	v_xor_b32_e32 v132, 0x80000000, v132
	v_mul_f32_dpp v2, v96, v2 row_newbcast:0 row_mask:0xf bank_mask:0xf
	v_mul_f32_dpp v3, v97, v3 row_newbcast:0 row_mask:0xf bank_mask:0xf
	v_mul_f32_dpp v4, v98, v4 row_newbcast:0 row_mask:0xf bank_mask:0xf
	v_mul_f32_dpp v5, v99, v5 row_newbcast:0 row_mask:0xf bank_mask:0xf
	v_fmac_f32_dpp v2, v100, v132 row_newbcast:0 row_mask:0xf bank_mask:0xf
	v_fmac_f32_dpp v3, v101, v132 row_newbcast:0 row_mask:0xf bank_mask:0xf
	v_fmac_f32_dpp v4, v102, v132 row_newbcast:0 row_mask:0xf bank_mask:0xf
	v_fmac_f32_dpp v5, v103, v132 row_newbcast:0 row_mask:0xf bank_mask:0xf
	v_mul_f32_dpp v128, v104, v2 row_newbcast:0 row_mask:0xf bank_mask:0xf
	v_mul_f32_dpp v129, v105, v3 row_newbcast:0 row_mask:0xf bank_mask:0xf
	v_mul_f32_dpp v130, v106, v4 row_newbcast:0 row_mask:0xf bank_mask:0xf
	v_mul_f32_dpp v131, v107, v5 row_newbcast:0 row_mask:0xf bank_mask:0xf
	v_mul_f32_dpp v6, v96, v6 row_newbcast:1 row_mask:0xf bank_mask:0xf
	v_mul_f32_dpp v7, v97, v7 row_newbcast:1 row_mask:0xf bank_mask:0xf
	v_mul_f32_dpp v8, v98, v8 row_newbcast:1 row_mask:0xf bank_mask:0xf
	v_mul_f32_dpp v9, v99, v9 row_newbcast:1 row_mask:0xf bank_mask:0xf
	v_fmac_f32_dpp v6, v100, v132 row_newbcast:1 row_mask:0xf bank_mask:0xf
	v_fmac_f32_dpp v7, v101, v132 row_newbcast:1 row_mask:0xf bank_mask:0xf
	v_fmac_f32_dpp v8, v102, v132 row_newbcast:1 row_mask:0xf bank_mask:0xf
	v_fmac_f32_dpp v9, v103, v132 row_newbcast:1 row_mask:0xf bank_mask:0xf
	v_fmac_f32_dpp v128, v104, v6 row_newbcast:1 row_mask:0xf bank_mask:0xf
	v_fmac_f32_dpp v129, v105, v7 row_newbcast:1 row_mask:0xf bank_mask:0xf
	v_fmac_f32_dpp v130, v106, v8 row_newbcast:1 row_mask:0xf bank_mask:0xf
	v_fmac_f32_dpp v131, v107, v9 row_newbcast:1 row_mask:0xf bank_mask:0xf
	v_mul_f32_dpp v10, v96, v10 row_newbcast:2 row_mask:0xf bank_mask:0xf
	v_mul_f32_dpp v11, v97, v11 row_newbcast:2 row_mask:0xf bank_mask:0xf
	v_mul_f32_dpp v12, v98, v12 row_newbcast:2 row_mask:0xf bank_mask:0xf
	v_mul_f32_dpp v13, v99, v13 row_newbcast:2 row_mask:0xf bank_mask:0xf
	v_fmac_f32_dpp v10, v100, v132 row_newbcast:2 row_mask:0xf bank_mask:0xf
	v_fmac_f32_dpp v11, v101, v132 row_newbcast:2 row_mask:0xf bank_mask:0xf
	v_fmac_f32_dpp v12, v102, v132 row_newbcast:2 row_mask:0xf bank_mask:0xf
	v_fmac_f32_dpp v13, v103, v132 row_newbcast:2 row_mask:0xf bank_mask:0xf
	v_fmac_f32_dpp v128, v104, v10 row_newbcast:2 row_mask:0xf bank_mask:0xf
	v_fmac_f32_dpp v129, v105, v11 row_newbcast:2 row_mask:0xf bank_mask:0xf
	v_fmac_f32_dpp v130, v106, v12 row_newbcast:2 row_mask:0xf bank_mask:0xf
	v_fmac_f32_dpp v131, v107, v13 row_newbcast:2 row_mask:0xf bank_mask:0xf
	v_mul_f32_dpp v14, v96, v14 row_newbcast:3 row_mask:0xf bank_mask:0xf
	v_mul_f32_dpp v15, v97, v15 row_newbcast:3 row_mask:0xf bank_mask:0xf
	v_mul_f32_dpp v16, v98, v16 row_newbcast:3 row_mask:0xf bank_mask:0xf
	v_mul_f32_dpp v17, v99, v17 row_newbcast:3 row_mask:0xf bank_mask:0xf
	v_fmac_f32_dpp v14, v100, v132 row_newbcast:3 row_mask:0xf bank_mask:0xf
	v_fmac_f32_dpp v15, v101, v132 row_newbcast:3 row_mask:0xf bank_mask:0xf
	v_fmac_f32_dpp v16, v102, v132 row_newbcast:3 row_mask:0xf bank_mask:0xf
	v_fmac_f32_dpp v17, v103, v132 row_newbcast:3 row_mask:0xf bank_mask:0xf
	v_fmac_f32_dpp v128, v104, v14 row_newbcast:3 row_mask:0xf bank_mask:0xf
	v_fmac_f32_dpp v129, v105, v15 row_newbcast:3 row_mask:0xf bank_mask:0xf
	v_fmac_f32_dpp v130, v106, v16 row_newbcast:3 row_mask:0xf bank_mask:0xf
	v_fmac_f32_dpp v131, v107, v17 row_newbcast:3 row_mask:0xf bank_mask:0xf
	v_mul_f32_dpp v18, v96, v18 row_newbcast:4 row_mask:0xf bank_mask:0xf
	v_mul_f32_dpp v19, v97, v19 row_newbcast:4 row_mask:0xf bank_mask:0xf
	v_mul_f32_dpp v20, v98, v20 row_newbcast:4 row_mask:0xf bank_mask:0xf
	v_mul_f32_dpp v21, v99, v21 row_newbcast:4 row_mask:0xf bank_mask:0xf
	v_fmac_f32_dpp v18, v100, v132 row_newbcast:4 row_mask:0xf bank_mask:0xf
	v_fmac_f32_dpp v19, v101, v132 row_newbcast:4 row_mask:0xf bank_mask:0xf
	v_fmac_f32_dpp v20, v102, v132 row_newbcast:4 row_mask:0xf bank_mask:0xf
	v_fmac_f32_dpp v21, v103, v132 row_newbcast:4 row_mask:0xf bank_mask:0xf
	v_fmac_f32_dpp v128, v104, v18 row_newbcast:4 row_mask:0xf bank_mask:0xf
	v_fmac_f32_dpp v129, v105, v19 row_newbcast:4 row_mask:0xf bank_mask:0xf
	v_fmac_f32_dpp v130, v106, v20 row_newbcast:4 row_mask:0xf bank_mask:0xf
	v_fmac_f32_dpp v131, v107, v21 row_newbcast:4 row_mask:0xf bank_mask:0xf
	v_mul_f32_dpp v22, v96, v22 row_newbcast:5 row_mask:0xf bank_mask:0xf
	v_mul_f32_dpp v23, v97, v23 row_newbcast:5 row_mask:0xf bank_mask:0xf
	v_mul_f32_dpp v24, v98, v24 row_newbcast:5 row_mask:0xf bank_mask:0xf
	v_mul_f32_dpp v25, v99, v25 row_newbcast:5 row_mask:0xf bank_mask:0xf
	v_fmac_f32_dpp v22, v100, v132 row_newbcast:5 row_mask:0xf bank_mask:0xf
	v_fmac_f32_dpp v23, v101, v132 row_newbcast:5 row_mask:0xf bank_mask:0xf
	v_fmac_f32_dpp v24, v102, v132 row_newbcast:5 row_mask:0xf bank_mask:0xf
	v_fmac_f32_dpp v25, v103, v132 row_newbcast:5 row_mask:0xf bank_mask:0xf
	v_fmac_f32_dpp v128, v104, v22 row_newbcast:5 row_mask:0xf bank_mask:0xf
	v_fmac_f32_dpp v129, v105, v23 row_newbcast:5 row_mask:0xf bank_mask:0xf
	v_fmac_f32_dpp v130, v106, v24 row_newbcast:5 row_mask:0xf bank_mask:0xf
	v_fmac_f32_dpp v131, v107, v25 row_newbcast:5 row_mask:0xf bank_mask:0xf
	v_mul_f32_dpp v26, v96, v26 row_newbcast:6 row_mask:0xf bank_mask:0xf
	v_mul_f32_dpp v27, v97, v27 row_newbcast:6 row_mask:0xf bank_mask:0xf
	v_mul_f32_dpp v28, v98, v28 row_newbcast:6 row_mask:0xf bank_mask:0xf
	v_mul_f32_dpp v29, v99, v29 row_newbcast:6 row_mask:0xf bank_mask:0xf
	v_fmac_f32_dpp v26, v100, v132 row_newbcast:6 row_mask:0xf bank_mask:0xf
; template <bool SK>
; __device__ __forceinline__ void scan_task(const float* R, const float* W, const float* KX, const float* KK, const float* KKA, const float* V, float* OUT, float* STT, const float* S0, float* SOUT, int nstep, int lane) {
;     ...
;         const float nd = -(d0 + d1);
;         const float vt = SK ? V[(size_t)t * BW + lane] : 0.f;
;         float o0 = 0.f, o1 = 0.f;
; #pragma unroll
;         for (int k = 0; k < 64; k += 2) {
;             float x = s[k] * w[k]; x = fmaf(nd, kka[k], x); if (SK) x = fmaf(vt, kx[k], x); s[k] = x; o0 = fmaf(x, r[k], o0);
;             float y = s[k + 1] * w[k + 1]; y = fmaf(nd, kka[k + 1], y); if (SK) y = fmaf(vt, kx[k + 1], y); s[k + 1] = y; o1 = fmaf(y, r[k + 1], o1);
	v_fmac_f32_dpp v27, v101, v132 row_newbcast:6 row_mask:0xf bank_mask:0xf
	v_fmac_f32_dpp v28, v102, v132 row_newbcast:6 row_mask:0xf bank_mask:0xf
	v_fmac_f32_dpp v29, v103, v132 row_newbcast:6 row_mask:0xf bank_mask:0xf
	v_fmac_f32_dpp v128, v104, v26 row_newbcast:6 row_mask:0xf bank_mask:0xf
	v_fmac_f32_dpp v129, v105, v27 row_newbcast:6 row_mask:0xf bank_mask:0xf
	v_fmac_f32_dpp v130, v106, v28 row_newbcast:6 row_mask:0xf bank_mask:0xf
	v_fmac_f32_dpp v131, v107, v29 row_newbcast:6 row_mask:0xf bank_mask:0xf
	v_mul_f32_dpp v30, v96, v30 row_newbcast:7 row_mask:0xf bank_mask:0xf
	v_mul_f32_dpp v31, v97, v31 row_newbcast:7 row_mask:0xf bank_mask:0xf
	v_mul_f32_dpp v32, v98, v32 row_newbcast:7 row_mask:0xf bank_mask:0xf
	v_mul_f32_dpp v33, v99, v33 row_newbcast:7 row_mask:0xf bank_mask:0xf
	v_fmac_f32_dpp v30, v100, v132 row_newbcast:7 row_mask:0xf bank_mask:0xf
	v_fmac_f32_dpp v31, v101, v132 row_newbcast:7 row_mask:0xf bank_mask:0xf
	v_fmac_f32_dpp v32, v102, v132 row_newbcast:7 row_mask:0xf bank_mask:0xf
	v_fmac_f32_dpp v33, v103, v132 row_newbcast:7 row_mask:0xf bank_mask:0xf
	v_fmac_f32_dpp v128, v104, v30 row_newbcast:7 row_mask:0xf bank_mask:0xf
	v_fmac_f32_dpp v129, v105, v31 row_newbcast:7 row_mask:0xf bank_mask:0xf
	v_fmac_f32_dpp v130, v106, v32 row_newbcast:7 row_mask:0xf bank_mask:0xf
	v_fmac_f32_dpp v131, v107, v33 row_newbcast:7 row_mask:0xf bank_mask:0xf
	v_mul_f32_dpp v36, v96, v36 row_newbcast:8 row_mask:0xf bank_mask:0xf
	v_mul_f32_dpp v37, v97, v37 row_newbcast:8 row_mask:0xf bank_mask:0xf
	v_mul_f32_dpp v38, v98, v38 row_newbcast:8 row_mask:0xf bank_mask:0xf
	v_mul_f32_dpp v39, v99, v39 row_newbcast:8 row_mask:0xf bank_mask:0xf
	v_fmac_f32_dpp v36, v100, v132 row_newbcast:8 row_mask:0xf bank_mask:0xf
	v_fmac_f32_dpp v37, v101, v132 row_newbcast:8 row_mask:0xf bank_mask:0xf
	v_fmac_f32_dpp v38, v102, v132 row_newbcast:8 row_mask:0xf bank_mask:0xf
	v_fmac_f32_dpp v39, v103, v132 row_newbcast:8 row_mask:0xf bank_mask:0xf
	v_fmac_f32_dpp v128, v104, v36 row_newbcast:8 row_mask:0xf bank_mask:0xf
	v_fmac_f32_dpp v129, v105, v37 row_newbcast:8 row_mask:0xf bank_mask:0xf
	v_fmac_f32_dpp v130, v106, v38 row_newbcast:8 row_mask:0xf bank_mask:0xf
	v_fmac_f32_dpp v131, v107, v39 row_newbcast:8 row_mask:0xf bank_mask:0xf
	v_mul_f32_dpp v40, v96, v40 row_newbcast:9 row_mask:0xf bank_mask:0xf
	v_mul_f32_dpp v41, v97, v41 row_newbcast:9 row_mask:0xf bank_mask:0xf
	v_mul_f32_dpp v42, v98, v42 row_newbcast:9 row_mask:0xf bank_mask:0xf
	v_mul_f32_dpp v43, v99, v43 row_newbcast:9 row_mask:0xf bank_mask:0xf
	v_fmac_f32_dpp v40, v100, v132 row_newbcast:9 row_mask:0xf bank_mask:0xf
	v_fmac_f32_dpp v41, v101, v132 row_newbcast:9 row_mask:0xf bank_mask:0xf
	v_fmac_f32_dpp v42, v102, v132 row_newbcast:9 row_mask:0xf bank_mask:0xf
	v_fmac_f32_dpp v43, v103, v132 row_newbcast:9 row_mask:0xf bank_mask:0xf
	v_fmac_f32_dpp v128, v104, v40 row_newbcast:9 row_mask:0xf bank_mask:0xf
	v_fmac_f32_dpp v129, v105, v41 row_newbcast:9 row_mask:0xf bank_mask:0xf
	v_fmac_f32_dpp v130, v106, v42 row_newbcast:9 row_mask:0xf bank_mask:0xf
	v_fmac_f32_dpp v131, v107, v43 row_newbcast:9 row_mask:0xf bank_mask:0xf
	v_mul_f32_dpp v44, v96, v44 row_newbcast:10 row_mask:0xf bank_mask:0xf
	v_mul_f32_dpp v45, v97, v45 row_newbcast:10 row_mask:0xf bank_mask:0xf
	v_mul_f32_dpp v46, v98, v46 row_newbcast:10 row_mask:0xf bank_mask:0xf
	v_mul_f32_dpp v47, v99, v47 row_newbcast:10 row_mask:0xf bank_mask:0xf
	v_fmac_f32_dpp v44, v100, v132 row_newbcast:10 row_mask:0xf bank_mask:0xf
	v_fmac_f32_dpp v45, v101, v132 row_newbcast:10 row_mask:0xf bank_mask:0xf
	v_fmac_f32_dpp v46, v102, v132 row_newbcast:10 row_mask:0xf bank_mask:0xf
	v_fmac_f32_dpp v47, v103, v132 row_newbcast:10 row_mask:0xf bank_mask:0xf
	v_fmac_f32_dpp v128, v104, v44 row_newbcast:10 row_mask:0xf bank_mask:0xf
	v_fmac_f32_dpp v129, v105, v45 row_newbcast:10 row_mask:0xf bank_mask:0xf
	v_fmac_f32_dpp v130, v106, v46 row_newbcast:10 row_mask:0xf bank_mask:0xf
	v_fmac_f32_dpp v131, v107, v47 row_newbcast:10 row_mask:0xf bank_mask:0xf
	v_mul_f32_dpp v48, v96, v48 row_newbcast:11 row_mask:0xf bank_mask:0xf
	v_mul_f32_dpp v49, v97, v49 row_newbcast:11 row_mask:0xf bank_mask:0xf
	v_mul_f32_dpp v50, v98, v50 row_newbcast:11 row_mask:0xf bank_mask:0xf
	v_mul_f32_dpp v51, v99, v51 row_newbcast:11 row_mask:0xf bank_mask:0xf
	v_fmac_f32_dpp v48, v100, v132 row_newbcast:11 row_mask:0xf bank_mask:0xf
	v_fmac_f32_dpp v49, v101, v132 row_newbcast:11 row_mask:0xf bank_mask:0xf
	v_fmac_f32_dpp v50, v102, v132 row_newbcast:11 row_mask:0xf bank_mask:0xf
	v_fmac_f32_dpp v51, v103, v132 row_newbcast:11 row_mask:0xf bank_mask:0xf
	v_fmac_f32_dpp v128, v104, v48 row_newbcast:11 row_mask:0xf bank_mask:0xf
	v_fmac_f32_dpp v129, v105, v49 row_newbcast:11 row_mask:0xf bank_mask:0xf
	v_fmac_f32_dpp v130, v106, v50 row_newbcast:11 row_mask:0xf bank_mask:0xf
	v_fmac_f32_dpp v131, v107, v51 row_newbcast:11 row_mask:0xf bank_mask:0xf
	v_mul_f32_dpp v52, v96, v52 row_newbcast:12 row_mask:0xf bank_mask:0xf
	v_mul_f32_dpp v53, v97, v53 row_newbcast:12 row_mask:0xf bank_mask:0xf
	v_mul_f32_dpp v54, v98, v54 row_newbcast:12 row_mask:0xf bank_mask:0xf
	v_mul_f32_dpp v55, v99, v55 row_newbcast:12 row_mask:0xf bank_mask:0xf
	v_fmac_f32_dpp v52, v100, v132 row_newbcast:12 row_mask:0xf bank_mask:0xf
	v_fmac_f32_dpp v53, v101, v132 row_newbcast:12 row_mask:0xf bank_mask:0xf
	v_fmac_f32_dpp v54, v102, v132 row_newbcast:12 row_mask:0xf bank_mask:0xf
	v_fmac_f32_dpp v55, v103, v132 row_newbcast:12 row_mask:0xf bank_mask:0xf
	v_fmac_f32_dpp v128, v104, v52 row_newbcast:12 row_mask:0xf bank_mask:0xf
	v_fmac_f32_dpp v129, v105, v53 row_newbcast:12 row_mask:0xf bank_mask:0xf
; template <bool SK>
; __device__ __forceinline__ void scan_task(const float* R, const float* W, const float* KX, const float* KK, const float* KKA, const float* V, float* OUT, float* STT, const float* S0, float* SOUT, int nstep, int lane) {
;     ...
;         { const int tp = (t + 2 < nstep) ? t + 2 : t; const size_t po = (size_t)tp * BW + lane;
;           pf0 = KK[po]; pf1 = W[po]; pf2 = KKA[po]; pf3 = KX[po]; pf4 = R[po]; }
;         cfloat* kk = (cfloat*)(KK + (size_t)t * BW); cfloat* w = (cfloat*)(W + (size_t)t * BW); cfloat* kka = (cfloat*)(KKA + (size_t)t * BW);
;         cfloat* kx = (cfloat*)(KX + (size_t)t * BW); cfloat* r = (cfloat*)(R + (size_t)t * BW);
;         float d0 = 0.f, d1 = 0.f;
; #pragma unroll
;         for (int k = 0; k < 64; k += 2) { d0 = fmaf(s[k], kk[k], d0); d1 = fmaf(s[k + 1], kk[k + 1], d1); }
;     ...
;         for (int k = 0; k < 64; k += 2) {
;             float x = s[k] * w[k]; x = fmaf(nd, kka[k], x); if (SK) x = fmaf(vt, kx[k], x); s[k] = x; o0 = fmaf(x, r[k], o0);
;             float y = s[k + 1] * w[k + 1]; y = fmaf(nd, kka[k + 1], y); if (SK) y = fmaf(vt, kx[k + 1], y); s[k + 1] = y; o1 = fmaf(y, r[k + 1], o1);
;         }
;         OUT[(size_t)t * BW + lane] = o0 + o1;
	v_fmac_f32_dpp v130, v106, v54 row_newbcast:12 row_mask:0xf bank_mask:0xf
	v_fmac_f32_dpp v131, v107, v55 row_newbcast:12 row_mask:0xf bank_mask:0xf
	v_mul_f32_dpp v56, v96, v56 row_newbcast:13 row_mask:0xf bank_mask:0xf
	v_mul_f32_dpp v57, v97, v57 row_newbcast:13 row_mask:0xf bank_mask:0xf
	v_mul_f32_dpp v58, v98, v58 row_newbcast:13 row_mask:0xf bank_mask:0xf
	v_mul_f32_dpp v59, v99, v59 row_newbcast:13 row_mask:0xf bank_mask:0xf
	v_fmac_f32_dpp v56, v100, v132 row_newbcast:13 row_mask:0xf bank_mask:0xf
	v_fmac_f32_dpp v57, v101, v132 row_newbcast:13 row_mask:0xf bank_mask:0xf
	v_fmac_f32_dpp v58, v102, v132 row_newbcast:13 row_mask:0xf bank_mask:0xf
	v_fmac_f32_dpp v59, v103, v132 row_newbcast:13 row_mask:0xf bank_mask:0xf
	v_fmac_f32_dpp v128, v104, v56 row_newbcast:13 row_mask:0xf bank_mask:0xf
	v_fmac_f32_dpp v129, v105, v57 row_newbcast:13 row_mask:0xf bank_mask:0xf
	v_fmac_f32_dpp v130, v106, v58 row_newbcast:13 row_mask:0xf bank_mask:0xf
	v_fmac_f32_dpp v131, v107, v59 row_newbcast:13 row_mask:0xf bank_mask:0xf
	v_mul_f32_dpp v60, v96, v60 row_newbcast:14 row_mask:0xf bank_mask:0xf
	v_mul_f32_dpp v61, v97, v61 row_newbcast:14 row_mask:0xf bank_mask:0xf
	v_mul_f32_dpp v62, v98, v62 row_newbcast:14 row_mask:0xf bank_mask:0xf
	v_mul_f32_dpp v63, v99, v63 row_newbcast:14 row_mask:0xf bank_mask:0xf
	v_fmac_f32_dpp v60, v100, v132 row_newbcast:14 row_mask:0xf bank_mask:0xf
	v_fmac_f32_dpp v61, v101, v132 row_newbcast:14 row_mask:0xf bank_mask:0xf
	v_fmac_f32_dpp v62, v102, v132 row_newbcast:14 row_mask:0xf bank_mask:0xf
	v_fmac_f32_dpp v63, v103, v132 row_newbcast:14 row_mask:0xf bank_mask:0xf
	v_fmac_f32_dpp v128, v104, v60 row_newbcast:14 row_mask:0xf bank_mask:0xf
	v_fmac_f32_dpp v129, v105, v61 row_newbcast:14 row_mask:0xf bank_mask:0xf
	v_fmac_f32_dpp v130, v106, v62 row_newbcast:14 row_mask:0xf bank_mask:0xf
	v_fmac_f32_dpp v131, v107, v63 row_newbcast:14 row_mask:0xf bank_mask:0xf
	v_mul_f32_dpp v64, v96, v64 row_newbcast:15 row_mask:0xf bank_mask:0xf
	v_mul_f32_dpp v65, v97, v65 row_newbcast:15 row_mask:0xf bank_mask:0xf
	v_mul_f32_dpp v66, v98, v66 row_newbcast:15 row_mask:0xf bank_mask:0xf
	v_mul_f32_dpp v67, v99, v67 row_newbcast:15 row_mask:0xf bank_mask:0xf
	v_fmac_f32_dpp v64, v100, v132 row_newbcast:15 row_mask:0xf bank_mask:0xf
	v_fmac_f32_dpp v65, v101, v132 row_newbcast:15 row_mask:0xf bank_mask:0xf
	v_fmac_f32_dpp v66, v102, v132 row_newbcast:15 row_mask:0xf bank_mask:0xf
	v_fmac_f32_dpp v67, v103, v132 row_newbcast:15 row_mask:0xf bank_mask:0xf
	v_fmac_f32_dpp v128, v104, v64 row_newbcast:15 row_mask:0xf bank_mask:0xf
	v_fmac_f32_dpp v129, v105, v65 row_newbcast:15 row_mask:0xf bank_mask:0xf
	v_fmac_f32_dpp v130, v106, v66 row_newbcast:15 row_mask:0xf bank_mask:0xf
	v_fmac_f32_dpp v131, v107, v67 row_newbcast:15 row_mask:0xf bank_mask:0xf
	global_load_dwordx4 v[96:99], v133, s[74:75]
	global_load_dwordx4 v[100:103], v133, s[76:77]
	global_load_dwordx4 v[104:107], v133, s[78:79]
	v_add_f32_e32 v128, v128, v130
	v_add_f32_e32 v129, v129, v131
	v_add_f32_e32 v128, v128, v129
	global_store_dword v134, v128, s[0:1]
	s_waitcnt vmcnt(6) lgkmcnt(0)
	v_pk_mul_f32 v[124:125], v[2:3], s[4:5]
	v_pk_mul_f32 v[126:127], v[4:5], s[6:7]
	v_pk_fma_f32 v[124:125], v[6:7], s[8:9], v[124:125]
	v_pk_fma_f32 v[126:127], v[8:9], s[10:11], v[126:127]
	v_pk_fma_f32 v[124:125], v[10:11], s[12:13], v[124:125]
	v_pk_fma_f32 v[126:127], v[12:13], s[14:15], v[126:127]
	v_pk_fma_f32 v[124:125], v[14:15], s[16:17], v[124:125]
	v_pk_fma_f32 v[126:127], v[16:17], s[18:19], v[126:127]
	v_pk_fma_f32 v[124:125], v[18:19], s[40:41], v[124:125]
	v_pk_fma_f32 v[126:127], v[20:21], s[42:43], v[126:127]
	v_pk_fma_f32 v[124:125], v[22:23], s[44:45], v[124:125]
	v_pk_fma_f32 v[126:127], v[24:25], s[46:47], v[126:127]
	v_pk_fma_f32 v[124:125], v[26:27], s[48:49], v[124:125]
	v_pk_fma_f32 v[126:127], v[28:29], s[50:51], v[126:127]
	v_pk_fma_f32 v[124:125], v[30:31], s[52:53], v[124:125]
	v_pk_fma_f32 v[126:127], v[32:33], s[54:55], v[126:127]
	v_pk_fma_f32 v[124:125], v[36:37], s[56:57], v[124:125]
	v_pk_fma_f32 v[126:127], v[38:39], s[58:59], v[126:127]
	v_pk_fma_f32 v[124:125], v[40:41], s[60:61], v[124:125]
	v_pk_fma_f32 v[126:127], v[42:43], s[62:63], v[126:127]
	v_pk_fma_f32 v[124:125], v[44:45], s[64:65], v[124:125]
	v_pk_fma_f32 v[126:127], v[46:47], s[66:67], v[126:127]
	v_pk_fma_f32 v[124:125], v[48:49], s[68:69], v[124:125]
	v_pk_fma_f32 v[126:127], v[50:51], s[70:71], v[126:127]
	s_nop 0
	v_fmac_f32_dpp v124, v108, v52 row_newbcast:12 row_mask:0xf bank_mask:0xf
	v_fmac_f32_dpp v125, v109, v53 row_newbcast:12 row_mask:0xf bank_mask:0xf
	v_fmac_f32_dpp v126, v110, v54 row_newbcast:12 row_mask:0xf bank_mask:0xf
	v_fmac_f32_dpp v127, v111, v55 row_newbcast:12 row_mask:0xf bank_mask:0xf
	v_fmac_f32_dpp v124, v108, v56 row_newbcast:13 row_mask:0xf bank_mask:0xf
	v_fmac_f32_dpp v125, v109, v57 row_newbcast:13 row_mask:0xf bank_mask:0xf
	v_fmac_f32_dpp v126, v110, v58 row_newbcast:13 row_mask:0xf bank_mask:0xf
	v_fmac_f32_dpp v127, v111, v59 row_newbcast:13 row_mask:0xf bank_mask:0xf
	v_fmac_f32_dpp v124, v108, v60 row_newbcast:14 row_mask:0xf bank_mask:0xf
	v_fmac_f32_dpp v125, v109, v61 row_newbcast:14 row_mask:0xf bank_mask:0xf
	v_fmac_f32_dpp v126, v110, v62 row_newbcast:14 row_mask:0xf bank_mask:0xf
	v_fmac_f32_dpp v127, v111, v63 row_newbcast:14 row_mask:0xf bank_mask:0xf
	v_fmac_f32_dpp v124, v108, v64 row_newbcast:15 row_mask:0xf bank_mask:0xf
	v_fmac_f32_dpp v125, v109, v65 row_newbcast:15 row_mask:0xf bank_mask:0xf
	v_fmac_f32_dpp v126, v110, v66 row_newbcast:15 row_mask:0xf bank_mask:0xf
	v_fmac_f32_dpp v127, v111, v67 row_newbcast:15 row_mask:0xf bank_mask:0xf
; template <bool SK>
; __device__ __forceinline__ void scan_task(const float* R, const float* W, const float* KX, const float* KK, const float* KKA, const float* V, float* OUT, float* STT, const float* S0, float* SOUT, int nstep, int lane) {
;     ...
;         { const int tp = (t + 2 < nstep) ? t + 2 : t; const size_t po = (size_t)tp * BW + lane;
;           pf0 = KK[po]; pf1 = W[po]; pf2 = KKA[po]; pf3 = KX[po]; pf4 = R[po]; }
;         cfloat* kk = (cfloat*)(KK + (size_t)t * BW); cfloat* w = (cfloat*)(W + (size_t)t * BW); cfloat* kka = (cfloat*)(KKA + (size_t)t * BW);
;         cfloat* kx = (cfloat*)(KX + (size_t)t * BW); cfloat* r = (cfloat*)(R + (size_t)t * BW);
;         float d0 = 0.f, d1 = 0.f;
; #pragma unroll
;         for (int k = 0; k < 64; k += 2) { d0 = fmaf(s[k], kk[k], d0); d1 = fmaf(s[k + 1], kk[k + 1], d1); }
;         const float nd = -(d0 + d1);
;         const float vt = SK ? V[(size_t)t * BW + lane] : 0.f;
;         float o0 = 0.f, o1 = 0.f;
; #pragma unroll
;         for (int k = 0; k < 64; k += 2) {
;             float x = s[k] * w[k]; x = fmaf(nd, kka[k], x); if (SK) x = fmaf(vt, kx[k], x); s[k] = x; o0 = fmaf(x, r[k], o0);
;             float y = s[k + 1] * w[k + 1]; y = fmaf(nd, kka[k + 1], y); if (SK) y = fmaf(vt, kx[k + 1], y); s[k + 1] = y; o1 = fmaf(y, r[k + 1], o1);
	global_load_dwordx4 v[108:111], v133, s[72:73] offset:2048
	s_add_u32 s2, s2, 0x800
	s_addc_u32 s3, s3, 0
	s_nop 1
	s_load_dwordx16 s[4:19], s[2:3], 0x0
	s_load_dwordx16 s[40:55], s[2:3], 0x40
	s_load_dwordx16 s[56:71], s[2:3], 0x80
	v_add_f32_e32 v124, v124, v126
	v_add_f32_e32 v125, v125, v127
	v_add_f32_e32 v132, v124, v125
	v_xor_b32_e32 v132, 0x80000000, v132
	v_mul_f32_dpp v2, v112, v2 row_newbcast:0 row_mask:0xf bank_mask:0xf
	v_mul_f32_dpp v3, v113, v3 row_newbcast:0 row_mask:0xf bank_mask:0xf
	v_mul_f32_dpp v4, v114, v4 row_newbcast:0 row_mask:0xf bank_mask:0xf
	v_mul_f32_dpp v5, v115, v5 row_newbcast:0 row_mask:0xf bank_mask:0xf
	v_fmac_f32_dpp v2, v116, v132 row_newbcast:0 row_mask:0xf bank_mask:0xf
	v_fmac_f32_dpp v3, v117, v132 row_newbcast:0 row_mask:0xf bank_mask:0xf
	v_fmac_f32_dpp v4, v118, v132 row_newbcast:0 row_mask:0xf bank_mask:0xf
	v_fmac_f32_dpp v5, v119, v132 row_newbcast:0 row_mask:0xf bank_mask:0xf
	v_mul_f32_dpp v128, v120, v2 row_newbcast:0 row_mask:0xf bank_mask:0xf
	v_mul_f32_dpp v129, v121, v3 row_newbcast:0 row_mask:0xf bank_mask:0xf
	v_mul_f32_dpp v130, v122, v4 row_newbcast:0 row_mask:0xf bank_mask:0xf
	v_mul_f32_dpp v131, v123, v5 row_newbcast:0 row_mask:0xf bank_mask:0xf
	v_mul_f32_dpp v6, v112, v6 row_newbcast:1 row_mask:0xf bank_mask:0xf
	v_mul_f32_dpp v7, v113, v7 row_newbcast:1 row_mask:0xf bank_mask:0xf
	v_mul_f32_dpp v8, v114, v8 row_newbcast:1 row_mask:0xf bank_mask:0xf
	v_mul_f32_dpp v9, v115, v9 row_newbcast:1 row_mask:0xf bank_mask:0xf
	v_fmac_f32_dpp v6, v116, v132 row_newbcast:1 row_mask:0xf bank_mask:0xf
	v_fmac_f32_dpp v7, v117, v132 row_newbcast:1 row_mask:0xf bank_mask:0xf
	v_fmac_f32_dpp v8, v118, v132 row_newbcast:1 row_mask:0xf bank_mask:0xf
	v_fmac_f32_dpp v9, v119, v132 row_newbcast:1 row_mask:0xf bank_mask:0xf
	v_fmac_f32_dpp v128, v120, v6 row_newbcast:1 row_mask:0xf bank_mask:0xf
	v_fmac_f32_dpp v129, v121, v7 row_newbcast:1 row_mask:0xf bank_mask:0xf
	v_fmac_f32_dpp v130, v122, v8 row_newbcast:1 row_mask:0xf bank_mask:0xf
	v_fmac_f32_dpp v131, v123, v9 row_newbcast:1 row_mask:0xf bank_mask:0xf
	v_mul_f32_dpp v10, v112, v10 row_newbcast:2 row_mask:0xf bank_mask:0xf
	v_mul_f32_dpp v11, v113, v11 row_newbcast:2 row_mask:0xf bank_mask:0xf
	v_mul_f32_dpp v12, v114, v12 row_newbcast:2 row_mask:0xf bank_mask:0xf
	v_mul_f32_dpp v13, v115, v13 row_newbcast:2 row_mask:0xf bank_mask:0xf
	v_fmac_f32_dpp v10, v116, v132 row_newbcast:2 row_mask:0xf bank_mask:0xf
	v_fmac_f32_dpp v11, v117, v132 row_newbcast:2 row_mask:0xf bank_mask:0xf
	v_fmac_f32_dpp v12, v118, v132 row_newbcast:2 row_mask:0xf bank_mask:0xf
	v_fmac_f32_dpp v13, v119, v132 row_newbcast:2 row_mask:0xf bank_mask:0xf
	v_fmac_f32_dpp v128, v120, v10 row_newbcast:2 row_mask:0xf bank_mask:0xf
	v_fmac_f32_dpp v129, v121, v11 row_newbcast:2 row_mask:0xf bank_mask:0xf
	v_fmac_f32_dpp v130, v122, v12 row_newbcast:2 row_mask:0xf bank_mask:0xf
	v_fmac_f32_dpp v131, v123, v13 row_newbcast:2 row_mask:0xf bank_mask:0xf
	v_mul_f32_dpp v14, v112, v14 row_newbcast:3 row_mask:0xf bank_mask:0xf
	v_mul_f32_dpp v15, v113, v15 row_newbcast:3 row_mask:0xf bank_mask:0xf
	v_mul_f32_dpp v16, v114, v16 row_newbcast:3 row_mask:0xf bank_mask:0xf
	v_mul_f32_dpp v17, v115, v17 row_newbcast:3 row_mask:0xf bank_mask:0xf
	v_fmac_f32_dpp v14, v116, v132 row_newbcast:3 row_mask:0xf bank_mask:0xf
	v_fmac_f32_dpp v15, v117, v132 row_newbcast:3 row_mask:0xf bank_mask:0xf
	v_fmac_f32_dpp v16, v118, v132 row_newbcast:3 row_mask:0xf bank_mask:0xf
	v_fmac_f32_dpp v17, v119, v132 row_newbcast:3 row_mask:0xf bank_mask:0xf
	v_fmac_f32_dpp v128, v120, v14 row_newbcast:3 row_mask:0xf bank_mask:0xf
	v_fmac_f32_dpp v129, v121, v15 row_newbcast:3 row_mask:0xf bank_mask:0xf
	v_fmac_f32_dpp v130, v122, v16 row_newbcast:3 row_mask:0xf bank_mask:0xf
	v_fmac_f32_dpp v131, v123, v17 row_newbcast:3 row_mask:0xf bank_mask:0xf
	v_mul_f32_dpp v18, v112, v18 row_newbcast:4 row_mask:0xf bank_mask:0xf
	v_mul_f32_dpp v19, v113, v19 row_newbcast:4 row_mask:0xf bank_mask:0xf
	v_mul_f32_dpp v20, v114, v20 row_newbcast:4 row_mask:0xf bank_mask:0xf
	v_mul_f32_dpp v21, v115, v21 row_newbcast:4 row_mask:0xf bank_mask:0xf
	v_fmac_f32_dpp v18, v116, v132 row_newbcast:4 row_mask:0xf bank_mask:0xf
	v_fmac_f32_dpp v19, v117, v132 row_newbcast:4 row_mask:0xf bank_mask:0xf
	v_fmac_f32_dpp v20, v118, v132 row_newbcast:4 row_mask:0xf bank_mask:0xf
	v_fmac_f32_dpp v21, v119, v132 row_newbcast:4 row_mask:0xf bank_mask:0xf
	v_fmac_f32_dpp v128, v120, v18 row_newbcast:4 row_mask:0xf bank_mask:0xf
	v_fmac_f32_dpp v129, v121, v19 row_newbcast:4 row_mask:0xf bank_mask:0xf
	v_fmac_f32_dpp v130, v122, v20 row_newbcast:4 row_mask:0xf bank_mask:0xf
	v_fmac_f32_dpp v131, v123, v21 row_newbcast:4 row_mask:0xf bank_mask:0xf
	v_mul_f32_dpp v22, v112, v22 row_newbcast:5 row_mask:0xf bank_mask:0xf
	v_mul_f32_dpp v23, v113, v23 row_newbcast:5 row_mask:0xf bank_mask:0xf
	v_mul_f32_dpp v24, v114, v24 row_newbcast:5 row_mask:0xf bank_mask:0xf
	v_mul_f32_dpp v25, v115, v25 row_newbcast:5 row_mask:0xf bank_mask:0xf
	v_fmac_f32_dpp v22, v116, v132 row_newbcast:5 row_mask:0xf bank_mask:0xf
	v_fmac_f32_dpp v23, v117, v132 row_newbcast:5 row_mask:0xf bank_mask:0xf
	v_fmac_f32_dpp v24, v118, v132 row_newbcast:5 row_mask:0xf bank_mask:0xf
	v_fmac_f32_dpp v25, v119, v132 row_newbcast:5 row_mask:0xf bank_mask:0xf
	v_fmac_f32_dpp v128, v120, v22 row_newbcast:5 row_mask:0xf bank_mask:0xf
	v_fmac_f32_dpp v129, v121, v23 row_newbcast:5 row_mask:0xf bank_mask:0xf
	v_fmac_f32_dpp v130, v122, v24 row_newbcast:5 row_mask:0xf bank_mask:0xf
	v_fmac_f32_dpp v131, v123, v25 row_newbcast:5 row_mask:0xf bank_mask:0xf
; template <bool SK>
; __device__ __forceinline__ void scan_task(const float* R, const float* W, const float* KX, const float* KK, const float* KKA, const float* V, float* OUT, float* STT, const float* S0, float* SOUT, int nstep, int lane) {
;     ...
;         const float nd = -(d0 + d1);
;         const float vt = SK ? V[(size_t)t * BW + lane] : 0.f;
;         float o0 = 0.f, o1 = 0.f;
; #pragma unroll
;         for (int k = 0; k < 64; k += 2) {
;             float x = s[k] * w[k]; x = fmaf(nd, kka[k], x); if (SK) x = fmaf(vt, kx[k], x); s[k] = x; o0 = fmaf(x, r[k], o0);
;             float y = s[k + 1] * w[k + 1]; y = fmaf(nd, kka[k + 1], y); if (SK) y = fmaf(vt, kx[k + 1], y); s[k + 1] = y; o1 = fmaf(y, r[k + 1], o1);
	v_mul_f32_dpp v26, v112, v26 row_newbcast:6 row_mask:0xf bank_mask:0xf
	v_mul_f32_dpp v27, v113, v27 row_newbcast:6 row_mask:0xf bank_mask:0xf
	v_mul_f32_dpp v28, v114, v28 row_newbcast:6 row_mask:0xf bank_mask:0xf
	v_mul_f32_dpp v29, v115, v29 row_newbcast:6 row_mask:0xf bank_mask:0xf
	v_fmac_f32_dpp v26, v116, v132 row_newbcast:6 row_mask:0xf bank_mask:0xf
	v_fmac_f32_dpp v27, v117, v132 row_newbcast:6 row_mask:0xf bank_mask:0xf
	v_fmac_f32_dpp v28, v118, v132 row_newbcast:6 row_mask:0xf bank_mask:0xf
	v_fmac_f32_dpp v29, v119, v132 row_newbcast:6 row_mask:0xf bank_mask:0xf
	v_fmac_f32_dpp v128, v120, v26 row_newbcast:6 row_mask:0xf bank_mask:0xf
	v_fmac_f32_dpp v129, v121, v27 row_newbcast:6 row_mask:0xf bank_mask:0xf
	v_fmac_f32_dpp v130, v122, v28 row_newbcast:6 row_mask:0xf bank_mask:0xf
	v_fmac_f32_dpp v131, v123, v29 row_newbcast:6 row_mask:0xf bank_mask:0xf
	v_mul_f32_dpp v30, v112, v30 row_newbcast:7 row_mask:0xf bank_mask:0xf
	v_mul_f32_dpp v31, v113, v31 row_newbcast:7 row_mask:0xf bank_mask:0xf
	v_mul_f32_dpp v32, v114, v32 row_newbcast:7 row_mask:0xf bank_mask:0xf
	v_mul_f32_dpp v33, v115, v33 row_newbcast:7 row_mask:0xf bank_mask:0xf
	v_fmac_f32_dpp v30, v116, v132 row_newbcast:7 row_mask:0xf bank_mask:0xf
	v_fmac_f32_dpp v31, v117, v132 row_newbcast:7 row_mask:0xf bank_mask:0xf
	v_fmac_f32_dpp v32, v118, v132 row_newbcast:7 row_mask:0xf bank_mask:0xf
	v_fmac_f32_dpp v33, v119, v132 row_newbcast:7 row_mask:0xf bank_mask:0xf
	v_fmac_f32_dpp v128, v120, v30 row_newbcast:7 row_mask:0xf bank_mask:0xf
	v_fmac_f32_dpp v129, v121, v31 row_newbcast:7 row_mask:0xf bank_mask:0xf
	v_fmac_f32_dpp v130, v122, v32 row_newbcast:7 row_mask:0xf bank_mask:0xf
	v_fmac_f32_dpp v131, v123, v33 row_newbcast:7 row_mask:0xf bank_mask:0xf
	v_mul_f32_dpp v36, v112, v36 row_newbcast:8 row_mask:0xf bank_mask:0xf
	v_mul_f32_dpp v37, v113, v37 row_newbcast:8 row_mask:0xf bank_mask:0xf
	v_mul_f32_dpp v38, v114, v38 row_newbcast:8 row_mask:0xf bank_mask:0xf
	v_mul_f32_dpp v39, v115, v39 row_newbcast:8 row_mask:0xf bank_mask:0xf
	v_fmac_f32_dpp v36, v116, v132 row_newbcast:8 row_mask:0xf bank_mask:0xf
	v_fmac_f32_dpp v37, v117, v132 row_newbcast:8 row_mask:0xf bank_mask:0xf
	v_fmac_f32_dpp v38, v118, v132 row_newbcast:8 row_mask:0xf bank_mask:0xf
	v_fmac_f32_dpp v39, v119, v132 row_newbcast:8 row_mask:0xf bank_mask:0xf
	v_fmac_f32_dpp v128, v120, v36 row_newbcast:8 row_mask:0xf bank_mask:0xf
	v_fmac_f32_dpp v129, v121, v37 row_newbcast:8 row_mask:0xf bank_mask:0xf
	v_fmac_f32_dpp v130, v122, v38 row_newbcast:8 row_mask:0xf bank_mask:0xf
	v_fmac_f32_dpp v131, v123, v39 row_newbcast:8 row_mask:0xf bank_mask:0xf
	v_mul_f32_dpp v40, v112, v40 row_newbcast:9 row_mask:0xf bank_mask:0xf
	v_mul_f32_dpp v41, v113, v41 row_newbcast:9 row_mask:0xf bank_mask:0xf
	v_mul_f32_dpp v42, v114, v42 row_newbcast:9 row_mask:0xf bank_mask:0xf
	v_mul_f32_dpp v43, v115, v43 row_newbcast:9 row_mask:0xf bank_mask:0xf
	v_fmac_f32_dpp v40, v116, v132 row_newbcast:9 row_mask:0xf bank_mask:0xf
	v_fmac_f32_dpp v41, v117, v132 row_newbcast:9 row_mask:0xf bank_mask:0xf
	v_fmac_f32_dpp v42, v118, v132 row_newbcast:9 row_mask:0xf bank_mask:0xf
	v_fmac_f32_dpp v43, v119, v132 row_newbcast:9 row_mask:0xf bank_mask:0xf
	v_fmac_f32_dpp v128, v120, v40 row_newbcast:9 row_mask:0xf bank_mask:0xf
	v_fmac_f32_dpp v129, v121, v41 row_newbcast:9 row_mask:0xf bank_mask:0xf
	v_fmac_f32_dpp v130, v122, v42 row_newbcast:9 row_mask:0xf bank_mask:0xf
	v_fmac_f32_dpp v131, v123, v43 row_newbcast:9 row_mask:0xf bank_mask:0xf
	v_mul_f32_dpp v44, v112, v44 row_newbcast:10 row_mask:0xf bank_mask:0xf
	v_mul_f32_dpp v45, v113, v45 row_newbcast:10 row_mask:0xf bank_mask:0xf
	v_mul_f32_dpp v46, v114, v46 row_newbcast:10 row_mask:0xf bank_mask:0xf
	v_mul_f32_dpp v47, v115, v47 row_newbcast:10 row_mask:0xf bank_mask:0xf
	v_fmac_f32_dpp v44, v116, v132 row_newbcast:10 row_mask:0xf bank_mask:0xf
	v_fmac_f32_dpp v45, v117, v132 row_newbcast:10 row_mask:0xf bank_mask:0xf
	v_fmac_f32_dpp v46, v118, v132 row_newbcast:10 row_mask:0xf bank_mask:0xf
	v_fmac_f32_dpp v47, v119, v132 row_newbcast:10 row_mask:0xf bank_mask:0xf
	v_fmac_f32_dpp v128, v120, v44 row_newbcast:10 row_mask:0xf bank_mask:0xf
	v_fmac_f32_dpp v129, v121, v45 row_newbcast:10 row_mask:0xf bank_mask:0xf
	v_fmac_f32_dpp v130, v122, v46 row_newbcast:10 row_mask:0xf bank_mask:0xf
	v_fmac_f32_dpp v131, v123, v47 row_newbcast:10 row_mask:0xf bank_mask:0xf
	v_mul_f32_dpp v48, v112, v48 row_newbcast:11 row_mask:0xf bank_mask:0xf
	v_mul_f32_dpp v49, v113, v49 row_newbcast:11 row_mask:0xf bank_mask:0xf
	v_mul_f32_dpp v50, v114, v50 row_newbcast:11 row_mask:0xf bank_mask:0xf
	v_mul_f32_dpp v51, v115, v51 row_newbcast:11 row_mask:0xf bank_mask:0xf
	v_fmac_f32_dpp v48, v116, v132 row_newbcast:11 row_mask:0xf bank_mask:0xf
	v_fmac_f32_dpp v49, v117, v132 row_newbcast:11 row_mask:0xf bank_mask:0xf
	v_fmac_f32_dpp v50, v118, v132 row_newbcast:11 row_mask:0xf bank_mask:0xf
	v_fmac_f32_dpp v51, v119, v132 row_newbcast:11 row_mask:0xf bank_mask:0xf
	v_fmac_f32_dpp v128, v120, v48 row_newbcast:11 row_mask:0xf bank_mask:0xf
	v_fmac_f32_dpp v129, v121, v49 row_newbcast:11 row_mask:0xf bank_mask:0xf
	v_fmac_f32_dpp v130, v122, v50 row_newbcast:11 row_mask:0xf bank_mask:0xf
	v_fmac_f32_dpp v131, v123, v51 row_newbcast:11 row_mask:0xf bank_mask:0xf
	v_mul_f32_dpp v52, v112, v52 row_newbcast:12 row_mask:0xf bank_mask:0xf
	v_mul_f32_dpp v53, v113, v53 row_newbcast:12 row_mask:0xf bank_mask:0xf
	v_mul_f32_dpp v54, v114, v54 row_newbcast:12 row_mask:0xf bank_mask:0xf
	v_mul_f32_dpp v55, v115, v55 row_newbcast:12 row_mask:0xf bank_mask:0xf
	v_fmac_f32_dpp v52, v116, v132 row_newbcast:12 row_mask:0xf bank_mask:0xf
; template <bool SK>
; __device__ __forceinline__ void scan_task(const float* R, const float* W, const float* KX, const float* KK, const float* KKA, const float* V, float* OUT, float* STT, const float* S0, float* SOUT, int nstep, int lane) {
;     ...
;     for (int t = 0; t < nstep; ++t) {
;     ...
;         for (int k = 0; k < 64; k += 2) {
;             float x = s[k] * w[k]; x = fmaf(nd, kka[k], x); if (SK) x = fmaf(vt, kx[k], x); s[k] = x; o0 = fmaf(x, r[k], o0);
;             float y = s[k + 1] * w[k + 1]; y = fmaf(nd, kka[k + 1], y); if (SK) y = fmaf(vt, kx[k + 1], y); s[k + 1] = y; o1 = fmaf(y, r[k + 1], o1);
;         }
;         OUT[(size_t)t * BW + lane] = o0 + o1;
	v_fmac_f32_dpp v53, v117, v132 row_newbcast:12 row_mask:0xf bank_mask:0xf
	v_fmac_f32_dpp v54, v118, v132 row_newbcast:12 row_mask:0xf bank_mask:0xf
	v_fmac_f32_dpp v55, v119, v132 row_newbcast:12 row_mask:0xf bank_mask:0xf
	v_fmac_f32_dpp v128, v120, v52 row_newbcast:12 row_mask:0xf bank_mask:0xf
	v_fmac_f32_dpp v129, v121, v53 row_newbcast:12 row_mask:0xf bank_mask:0xf
	v_fmac_f32_dpp v130, v122, v54 row_newbcast:12 row_mask:0xf bank_mask:0xf
	v_fmac_f32_dpp v131, v123, v55 row_newbcast:12 row_mask:0xf bank_mask:0xf
	v_mul_f32_dpp v56, v112, v56 row_newbcast:13 row_mask:0xf bank_mask:0xf
	v_mul_f32_dpp v57, v113, v57 row_newbcast:13 row_mask:0xf bank_mask:0xf
	v_mul_f32_dpp v58, v114, v58 row_newbcast:13 row_mask:0xf bank_mask:0xf
	v_mul_f32_dpp v59, v115, v59 row_newbcast:13 row_mask:0xf bank_mask:0xf
	v_fmac_f32_dpp v56, v116, v132 row_newbcast:13 row_mask:0xf bank_mask:0xf
	v_fmac_f32_dpp v57, v117, v132 row_newbcast:13 row_mask:0xf bank_mask:0xf
	v_fmac_f32_dpp v58, v118, v132 row_newbcast:13 row_mask:0xf bank_mask:0xf
	v_fmac_f32_dpp v59, v119, v132 row_newbcast:13 row_mask:0xf bank_mask:0xf
	v_fmac_f32_dpp v128, v120, v56 row_newbcast:13 row_mask:0xf bank_mask:0xf
	v_fmac_f32_dpp v129, v121, v57 row_newbcast:13 row_mask:0xf bank_mask:0xf
	v_fmac_f32_dpp v130, v122, v58 row_newbcast:13 row_mask:0xf bank_mask:0xf
	v_fmac_f32_dpp v131, v123, v59 row_newbcast:13 row_mask:0xf bank_mask:0xf
	v_mul_f32_dpp v60, v112, v60 row_newbcast:14 row_mask:0xf bank_mask:0xf
	v_mul_f32_dpp v61, v113, v61 row_newbcast:14 row_mask:0xf bank_mask:0xf
	v_mul_f32_dpp v62, v114, v62 row_newbcast:14 row_mask:0xf bank_mask:0xf
	v_mul_f32_dpp v63, v115, v63 row_newbcast:14 row_mask:0xf bank_mask:0xf
	v_fmac_f32_dpp v60, v116, v132 row_newbcast:14 row_mask:0xf bank_mask:0xf
	v_fmac_f32_dpp v61, v117, v132 row_newbcast:14 row_mask:0xf bank_mask:0xf
	v_fmac_f32_dpp v62, v118, v132 row_newbcast:14 row_mask:0xf bank_mask:0xf
	v_fmac_f32_dpp v63, v119, v132 row_newbcast:14 row_mask:0xf bank_mask:0xf
	v_fmac_f32_dpp v128, v120, v60 row_newbcast:14 row_mask:0xf bank_mask:0xf
	v_fmac_f32_dpp v129, v121, v61 row_newbcast:14 row_mask:0xf bank_mask:0xf
	v_fmac_f32_dpp v130, v122, v62 row_newbcast:14 row_mask:0xf bank_mask:0xf
	v_fmac_f32_dpp v131, v123, v63 row_newbcast:14 row_mask:0xf bank_mask:0xf
	v_mul_f32_dpp v64, v112, v64 row_newbcast:15 row_mask:0xf bank_mask:0xf
	v_mul_f32_dpp v65, v113, v65 row_newbcast:15 row_mask:0xf bank_mask:0xf
	v_mul_f32_dpp v66, v114, v66 row_newbcast:15 row_mask:0xf bank_mask:0xf
	v_mul_f32_dpp v67, v115, v67 row_newbcast:15 row_mask:0xf bank_mask:0xf
	v_fmac_f32_dpp v64, v116, v132 row_newbcast:15 row_mask:0xf bank_mask:0xf
	v_fmac_f32_dpp v65, v117, v132 row_newbcast:15 row_mask:0xf bank_mask:0xf
	v_fmac_f32_dpp v66, v118, v132 row_newbcast:15 row_mask:0xf bank_mask:0xf
	v_fmac_f32_dpp v67, v119, v132 row_newbcast:15 row_mask:0xf bank_mask:0xf
	v_fmac_f32_dpp v128, v120, v64 row_newbcast:15 row_mask:0xf bank_mask:0xf
	v_fmac_f32_dpp v129, v121, v65 row_newbcast:15 row_mask:0xf bank_mask:0xf
	v_fmac_f32_dpp v130, v122, v66 row_newbcast:15 row_mask:0xf bank_mask:0xf
	v_fmac_f32_dpp v131, v123, v67 row_newbcast:15 row_mask:0xf bank_mask:0xf
	global_load_dwordx4 v[112:115], v133, s[74:75] offset:2048
	global_load_dwordx4 v[116:119], v133, s[76:77] offset:2048
	global_load_dwordx4 v[120:123], v133, s[78:79] offset:2048
	v_add_f32_e32 v128, v128, v130
	v_add_f32_e32 v129, v129, v131
	v_add_f32_e32 v128, v128, v129
	global_store_dword v134, v128, s[0:1] offset:2048
	s_add_u32 s72, s72, 0x1000
	s_addc_u32 s73, s73, 0
	s_add_u32 s74, s74, 0x1000
	s_addc_u32 s75, s75, 0
	s_add_u32 s76, s76, 0x1000
	s_addc_u32 s77, s77, 0
	s_add_u32 s78, s78, 0x1000
	s_addc_u32 s79, s79, 0
	s_add_u32 s0, s0, 0x1000
	s_addc_u32 s1, s1, 0
	s_add_i32 s20, s20, 1
	s_cmp_lg_u32 s20, 32
	s_cbranch_scc1 .Lscan_p_loop
; template <bool SK>
; __device__ __forceinline__ void scan_task(const float* R, const float* W, const float* KX, const float* KK, const float* KKA, const float* V, float* OUT, float* STT, const float* S0, float* SOUT, int nstep, int lane) {
;     ...
;     if (SOUT) {
; #pragma unroll
;         for (int k4 = 0; k4 < 16; ++k4) *(f32x4*)(SOUT + lane * 64 + 4 * k4) = (f32x4){s[4 * k4], s[4 * k4 + 1], s[4 * k4 + 2], s[4 * k4 + 3]};
;     }
	s_waitcnt vmcnt(0)
	v_mov_b32_e32 v1, v135
	s_nop 0
	ds_read_b32 v92, v1 offset:0
	ds_read_b32 v93, v1 offset:256
	ds_read_b32 v94, v1 offset:512
	ds_read_b32 v95, v1 offset:768
	ds_read_b32 v96, v1 offset:1024
	ds_read_b32 v97, v1 offset:1280
	ds_read_b32 v98, v1 offset:1536
	ds_read_b32 v99, v1 offset:1792
	ds_read_b32 v100, v1 offset:2048
	ds_read_b32 v101, v1 offset:2304
	ds_read_b32 v102, v1 offset:2560
	ds_read_b32 v103, v1 offset:2816
	ds_read_b32 v104, v1 offset:3072
	ds_read_b32 v105, v1 offset:3328
	ds_read_b32 v106, v1 offset:3584
	ds_read_b32 v107, v1 offset:3840
	ds_read_b32 v108, v1 offset:4096
	ds_read_b32 v109, v1 offset:4352
	ds_read_b32 v110, v1 offset:4608
	ds_read_b32 v111, v1 offset:4864
	ds_read_b32 v112, v1 offset:5120
	ds_read_b32 v113, v1 offset:5376
	ds_read_b32 v114, v1 offset:5632
	ds_read_b32 v115, v1 offset:5888
	ds_read_b32 v116, v1 offset:6144
	ds_read_b32 v117, v1 offset:6400
	ds_read_b32 v118, v1 offset:6656
	ds_read_b32 v119, v1 offset:6912
	ds_read_b32 v120, v1 offset:7168
	ds_read_b32 v121, v1 offset:7424
	ds_read_b32 v122, v1 offset:7680
	ds_read_b32 v123, v1 offset:7936
	ds_read_b32 v124, v1 offset:8192
	ds_read_b32 v125, v1 offset:8448
	ds_read_b32 v126, v1 offset:8704
	ds_read_b32 v127, v1 offset:8960
	ds_read_b32 v128, v1 offset:9216
	ds_read_b32 v129, v1 offset:9472
	ds_read_b32 v130, v1 offset:9728
	ds_read_b32 v131, v1 offset:9984
	ds_read_b32 v132, v1 offset:10240
	ds_read_b32 v133, v1 offset:10496
	ds_read_b32 v134, v1 offset:10752
	ds_read_b32 v135, v1 offset:11008
	s_waitcnt lgkmcnt(0)
	v_lshlrev_b64 v[70:71], 2, v[70:71]
	v_lshlrev_b32_e32 v68, 6, v68
	v_lshl_add_u64 v[70:71], s[82:83], 0, v[70:71]
	v_ashrrev_i32_e32 v69, 31, v68
	v_lshl_add_u64 v[68:69], v[68:69], 2, v[70:71]
	s_mov_b64 s[0:1], 0x43b00000
	v_lshl_add_u64 v[70:71], v[68:69], 0, s[0:1]
	v_add_co_u32_e32 v68, vcc, 0x43b00000, v68
	v_readlane_b32 s82, v254, 57
	v_readlane_b32 s84, v254, 59
	v_readlane_b32 s86, v254, 61
	v_readlane_b32 s88, v254, 63
	v_readlane_b32 s76, v255, 1
	v_readlane_b32 s78, v255, 3
	v_readlane_b32 s90, v255, 5
	v_readlane_b32 s56, v255, 7
	v_readlane_b32 s60, v255, 9
	v_readlane_b32 s74, v255, 15
	s_movk_i32 s64, 0xf800
	v_addc_co_u32_e32 v69, vcc, 0, v69, vcc
	v_readlane_b32 s83, v254, 58
	v_readlane_b32 s85, v254, 60
	v_readlane_b32 s87, v254, 62
	v_readlane_b32 s89, v255, 0
	v_readlane_b32 s77, v255, 2
	v_readlane_b32 s79, v255, 4
	v_readlane_b32 s91, v255, 6
	v_readlane_b32 s57, v255, 8
	v_readlane_b32 s61, v255, 10
	v_readlane_b32 s62, v255, 11
	v_readlane_b32 s63, v255, 12
	s_mov_b32 s67, 0xf800000
	s_movk_i32 s68, 0x2a00
	s_movk_i32 s69, 0x1000
	s_movk_i32 s70, 0x1c00
	s_mov_b32 s71, 0x92492493
	v_readlane_b32 s72, v255, 14
	v_readlane_b32 s75, v255, 16
	s_mov_b32 s65, -1
	v_readlane_b32 s66, v255, 22
	s_waitcnt vmcnt(0)
	global_store_dwordx4 v[68:69], v[2:5], off
	global_store_dwordx4 v[70:71], v[6:9], off offset:16
	global_store_dwordx4 v[70:71], v[10:13], off offset:32
	global_store_dwordx4 v[70:71], v[14:17], off offset:48
	global_store_dwordx4 v[70:71], v[18:21], off offset:64
	global_store_dwordx4 v[70:71], v[22:25], off offset:80
	global_store_dwordx4 v[70:71], v[26:29], off offset:96
	global_store_dwordx4 v[70:71], v[30:33], off offset:112
	global_store_dwordx4 v[70:71], v[36:39], off offset:128
	global_store_dwordx4 v[70:71], v[40:43], off offset:144
	global_store_dwordx4 v[70:71], v[44:47], off offset:160
	global_store_dwordx4 v[70:71], v[48:51], off offset:176
	global_store_dwordx4 v[70:71], v[52:55], off offset:192
	global_store_dwordx4 v[70:71], v[56:59], off offset:208
	global_store_dwordx4 v[70:71], v[60:63], off offset:224
	global_store_dwordx4 v[70:71], v[64:67], off offset:240
	s_branch .LBB0_903
